# R2 router software-pipelined: top-4 selection of the previous 16-row step interleaved with the router MFMAs of the current one, last selection after the loop
# baseline (speedup 1.0000x reference)
; #define LAS __attribute__((address_space(3)))
; __device__ __forceinline__ unsigned dpp_swap1(unsigned v) { return (unsigned)__builtin_amdgcn_update_dpp(0, (int)v, 0xB1, 0xF, 0xF, true); }
; __device__ __forceinline__ void unpack_row_raw(const RowRaw& r, int lane, v2u (&o)[4]) {
;     const bool odd = (lane & 1) != 0;
; #pragma unroll
;     for (int pr = 0; pr < 2; ++pr) { const v4u w = r.w[pr]; const v2u lo = (v2u){w.x, w.y}, hi = (v2u){w.z, w.w}, send = odd ? lo : hi; v2u recv; recv.x = dpp_swap1(send.x); recv.y = dpp_swap1(send.y);
;         o[2 * pr] = odd ? recv : lo; o[2 * pr + 1] = odd ? hi : recv; }
; }
; __device__ __forceinline__ void p_r2(const Args& a, LAS unsigned char* lds, volatile LAS unsigned* MISC, int l, int wg, int G, int wave, int lane, int tid) {
;     ...
;                 else { v2u xw[4]; unpack_row_raw(xpre[r], lane, xw);
; #pragma unroll
;                     for (int j = 0; j < 4; ++j) x[r][j] = (f32x4){bf_lo(xw[j].x), bf_hi(xw[j].x), bf_lo(xw[j].y), bf_hi(xw[j].y)}; }
;                 unpack_row_raw(mpre[r], lane, mw[r]); }
;             if (it + 1 < 16) {
; #pragma unroll
;                 for (int r = 0; r < 2; ++r) { load_row_raw(MIX + (size_t)(t0 + 16 + r) * D, lane, mpre[r]); if (l != 0) load_row_raw(xbf + (size_t)(t0 + 16 + r) * D, lane, xpre[r]); } }
; #pragma unroll
;             for (int j = 0; j < 4; ++j) { const f32x4 g1 = *(const LAS f32x4*)(lds + R2_PAR + (0 * 256 + lane + 64 * j) * 16);
; #pragma unroll
;                 for (int r = 0; r < 2; ++r) { const f32x4 mx = (f32x4){bf_lo(mw[r][j].x), bf_hi(mw[r][j].x), bf_lo(mw[r][j].y), bf_hi(mw[r][j].y)}; x[r][j] = ALPHA * x[r][j] + (1.0f + g1) * mx; } }
.LBB0_836:
	v_cndmask_b32_e64 v136, v188, v136, s[44:45]
	v_cndmask_b32_e64 v138, v138, v188, s[44:45]
	v_cndmask_b32_e64 v188, v191, v133, s[44:45]
	v_cndmask_b32_e64 v133, v18, v124, s[44:45]
	v_cndmask_b32_e64 v193, v126, v18, s[44:45]
	v_add_u32_e32 v18, 0, v156
	v_cndmask_b32_e64 v137, v190, v137, s[44:45]
	v_cndmask_b32_e64 v139, v139, v190, s[44:45]
	v_cndmask_b32_e64 v190, v189, v132, s[44:45]
	v_cndmask_b32_e64 v132, v186, v125, s[44:45]
	v_cndmask_b32_e64 v192, v127, v186, s[44:45]
	v_add_u32_e32 v186, 0x14800, v18
	v_cndmask_b32_e64 v194, v187, v121, s[44:45]
	v_cndmask_b32_e64 v195, v19, v120, s[44:45]
	v_cndmask_b32_e64 v187, v123, v187, s[44:45]
	v_cndmask_b32_e64 v196, v122, v19, s[44:45]
	ds_read_b128 v[120:123], v186
	v_lshlrev_b32_e32 v18, 16, v133
	v_and_b32_e32 v19, 0xffff0000, v133
	v_and_b32_e32 v133, 0xffff0000, v137
	v_lshlrev_b32_e32 v126, 16, v136
	s_waitcnt lgkmcnt(0)
	v_pk_add_f32 v[122:123], v[122:123], 1.0 op_sel_hi:[1,0]
	v_pk_add_f32 v[124:125], v[120:121], 1.0 op_sel_hi:[1,0]
	v_lshlrev_b32_e32 v120, 16, v132
	v_and_b32_e32 v121, 0xffff0000, v132
	v_lshlrev_b32_e32 v132, 16, v137
	v_and_b32_e32 v127, 0xffff0000, v136
	v_pk_mul_f32 v[132:133], v[122:123], v[132:133]
	v_cndmask_b32_e64 v191, v135, v191, s[44:45]
	v_cndmask_b32_e64 v189, v134, v189, s[44:45]
	v_pk_mul_f32 v[120:121], v[122:123], v[120:121]
	v_pk_mul_f32 v[18:19], v[124:125], v[18:19]
	v_pk_mul_f32 v[122:123], v[124:125], v[126:127]
	v_pk_fma_f32 v[124:125], v[150:151], s[10:11], v[132:133] op_sel_hi:[1,0,1]
	ds_read_b128 v[132:135], v186 offset:1024
	v_lshlrev_b32_e32 v126, 16, v193
	v_and_b32_e32 v127, 0xffff0000, v193
	v_pk_fma_f32 v[120:121], v[146:147], s[10:11], v[120:121] op_sel_hi:[1,0,1]
	v_pk_fma_f32 v[18:19], v[144:145], s[10:11], v[18:19] op_sel_hi:[1,0,1]
	s_waitcnt lgkmcnt(0)
	v_pk_add_f32 v[134:135], v[134:135], 1.0 op_sel_hi:[1,0]
	v_pk_add_f32 v[136:137], v[132:133], 1.0 op_sel_hi:[1,0]
	v_lshlrev_b32_e32 v132, 16, v192
	v_and_b32_e32 v133, 0xffff0000, v192
	v_pk_mul_f32 v[132:133], v[134:135], v[132:133]
	v_pk_mul_f32 v[126:127], v[136:137], v[126:127]
	v_pk_fma_f32 v[132:133], v[118:119], s[10:11], v[132:133] op_sel_hi:[1,0,1]
	v_pk_fma_f32 v[126:127], v[116:117], s[10:11], v[126:127] op_sel_hi:[1,0,1]
	v_lshlrev_b32_e32 v116, 16, v138
	v_and_b32_e32 v117, 0xffff0000, v138
	v_lshlrev_b32_e32 v118, 16, v139
	v_and_b32_e32 v119, 0xffff0000, v139
	v_pk_mul_f32 v[118:119], v[134:135], v[118:119]
	v_pk_mul_f32 v[116:117], v[136:137], v[116:117]
	ds_read_b128 v[134:137], v186 offset:2048
	v_pk_fma_f32 v[116:117], v[140:141], s[10:11], v[116:117] op_sel_hi:[1,0,1]
	v_lshlrev_b32_e32 v140, 16, v194
	v_and_b32_e32 v141, 0xffff0000, v194
	v_pk_fma_f32 v[122:123], v[148:149], s[10:11], v[122:123] op_sel_hi:[1,0,1]
	s_waitcnt lgkmcnt(0)
	v_pk_add_f32 v[136:137], v[136:137], 1.0 op_sel_hi:[1,0]
	v_pk_add_f32 v[138:139], v[134:135], 1.0 op_sel_hi:[1,0]
	v_lshlrev_b32_e32 v134, 16, v195
	v_and_b32_e32 v135, 0xffff0000, v195
	v_pk_mul_f32 v[134:135], v[138:139], v[134:135]
	v_pk_mul_f32 v[140:141], v[136:137], v[140:141]
	v_pk_fma_f32 v[134:135], v[112:113], s[10:11], v[134:135] op_sel_hi:[1,0,1]
	v_pk_fma_f32 v[114:115], v[114:115], s[10:11], v[140:141] op_sel_hi:[1,0,1]
	v_lshlrev_b32_e32 v112, 16, v190
	v_and_b32_e32 v113, 0xffff0000, v190
	v_lshlrev_b32_e32 v140, 16, v188
	v_and_b32_e32 v141, 0xffff0000, v188
	v_pk_mul_f32 v[138:139], v[138:139], v[112:113]
	v_pk_mul_f32 v[112:113], v[136:137], v[140:141]
	v_pk_fma_f32 v[136:137], v[128:129], s[10:11], v[138:139] op_sel_hi:[1,0,1]
	v_pk_fma_f32 v[112:113], v[130:131], s[10:11], v[112:113] op_sel_hi:[1,0,1]
	ds_read_b128 v[128:131], v186 offset:3072
	v_lshlrev_b32_e32 v138, 16, v196
	v_and_b32_e32 v139, 0xffff0000, v196
	v_lshlrev_b32_e32 v140, 16, v187
	v_and_b32_e32 v141, 0xffff0000, v187
	s_waitcnt lgkmcnt(0)
	v_pk_add_f32 v[128:129], v[128:129], 1.0 op_sel_hi:[1,0]
	v_pk_add_f32 v[130:131], v[130:131], 1.0 op_sel_hi:[1,0]
	v_pk_mul_f32 v[138:139], v[128:129], v[138:139]
	v_pk_mul_f32 v[140:141], v[130:131], v[140:141]
	v_pk_fma_f32 v[146:147], v[104:105], s[10:11], v[138:139] op_sel_hi:[1,0,1]
	v_lshlrev_b32_e32 v104, 16, v189
	v_and_b32_e32 v105, 0xffff0000, v189
	v_lshlrev_b32_e32 v138, 16, v191
	v_and_b32_e32 v139, 0xffff0000, v191
	v_pk_mul_f32 v[128:129], v[128:129], v[104:105]
	v_pk_mul_f32 v[104:105], v[130:131], v[138:139]
	v_pk_fma_f32 v[144:145], v[108:109], s[10:11], v[128:129] op_sel_hi:[1,0,1]
	v_pk_fma_f32 v[104:105], v[110:111], s[10:11], v[104:105] op_sel_hi:[1,0,1]
	v_pk_mov_b32 v[108:109], v[18:19], v[120:121] op_sel:[1,0]
	v_mov_b32_e32 v110, v18
	v_mov_b32_e32 v111, v121
	v_pk_add_f32 v[108:109], v[108:109], v[110:111]
	v_pk_mov_b32 v[110:111], v[126:127], v[132:133] op_sel:[1,0]
	v_mov_b32_e32 v128, v126
	v_mov_b32_e32 v129, v133
	v_pk_add_f32 v[110:111], v[110:111], v[128:129]
	v_pk_fma_f32 v[106:107], v[106:107], s[10:11], v[140:141] op_sel_hi:[1,0,1]
	v_add_f32_e32 v108, v108, v109
	v_pk_add_f32 v[110:111], v[110:111], v[110:111] op_sel:[0,1] op_sel_hi:[1,0]
	v_add_f32_e32 v108, 0, v108
	v_add_f32_e32 v128, v134, v135
	v_add_f32_e32 v130, v114, v115
	v_mov_b32_e32 v109, v146
	v_mov_b32_e32 v111, v147
	v_mov_b32_e32 v129, v106
	v_mov_b32_e32 v131, v107
	v_pk_add_f32 v[108:109], v[108:109], v[110:111]
	v_pk_add_f32 v[110:111], v[128:129], v[130:131]
	v_pk_fma_f32 v[118:119], v[142:143], s[10:11], v[118:119] op_sel_hi:[1,0,1]
	v_pk_add_f32 v[108:109], v[108:109], v[110:111]
	v_mov_b32_e32 v139, v105
	v_add_f32_e32 v108, v108, v109
	s_nop 1
	v_add_f32_dpp v108, v108, v108 quad_perm:[1,0,3,2] row_mask:0xf bank_mask:0xf bound_ctrl:1
	s_nop 1
; __device__ __forceinline__ void ln_stats(const f32x4 (&v)[4], float& mean, float& rstd) {
;     float s = 0.f;
; #pragma unroll
;     for (int j = 0; j < 4; ++j) s += (v[j][0] + v[j][1]) + (v[j][2] + v[j][3]);
;     mean = wave_sum(s) * (1.f / D); float q = 0.f;
; #pragma unroll
;     for (int j = 0; j < 4; ++j) { const f32x4 d = v[j] - mean; q += (d[0] * d[0] + d[1] * d[1]) + (d[2] * d[2] + d[3] * d[3]); }
;     rstd = rsqrtf(wave_sum(q) * (1.f / D) + LN_EPS);
; }
; __device__ __forceinline__ void p_r2(const Args& a, LAS unsigned char* lds, volatile LAS unsigned* MISC, int l, int wg, int G, int wave, int lane, int tid) {
;     ...
;             float mean[2], rstd[2];
; #pragma unroll
;             for (int r = 0; r < 2; ++r) ln_stats(x[r], mean[r], rstd[r]);
	v_add_f32_dpp v108, v108, v108 quad_perm:[2,3,0,1] row_mask:0xf bank_mask:0xf bound_ctrl:1
	s_nop 1
	v_add_f32_dpp v108, v108, v108 row_half_mirror row_mask:0xf bank_mask:0xf bound_ctrl:1
	s_nop 1
	v_add_f32_dpp v108, v108, v108 row_mirror row_mask:0xf bank_mask:0xf bound_ctrl:1
	s_nop 0
	v_readlane_b32 s4, v108, 16
	v_readlane_b32 s9, v108, 48
	v_readlane_b32 s2, v108, 0
	v_readlane_b32 s3, v108, 32
	v_mov_b32_e32 v108, s4
	v_mov_b32_e32 v109, s9
	v_pk_add_f32 v[108:109], s[2:3], v[108:109]
	s_nop 0
	v_add_f32_e32 v138, v108, v109
	v_fmamk_f32 v19, v138, 0xba800000, v19
	v_fmac_f32_e32 v18, 0xba800000, v138
	v_fmamk_f32 v121, v138, 0xba800000, v121
	v_fmac_f32_e32 v120, 0xba800000, v138
	v_pk_mul_f32 v[108:109], v[120:121], v[120:121]
	v_pk_mul_f32 v[110:111], v[18:19], v[18:19]
	v_fmamk_f32 v127, v138, 0xba800000, v127
	v_pk_mov_b32 v[128:129], v[110:111], v[108:109] op_sel:[1,0]
	v_mov_b32_e32 v111, v109
	v_pk_add_f32 v[108:109], v[128:129], v[110:111]
	v_fmac_f32_e32 v126, 0xba800000, v138
	v_fmamk_f32 v133, v138, 0xba800000, v133
	v_fmac_f32_e32 v132, 0xba800000, v138
	v_pk_add_f32 v[108:109], v[108:109], v[108:109] op_sel_hi:[0,1]
	v_pk_mul_f32 v[110:111], v[132:133], v[132:133]
	v_pk_mul_f32 v[128:129], v[126:127], v[126:127]
	v_fmac_f32_e32 v134, 0xba800000, v138
	v_pk_mov_b32 v[130:131], v[128:129], v[110:111] op_sel:[1,0]
	v_mov_b32_e32 v129, v111
	v_fmamk_f32 v135, v138, 0xba800000, v135
	v_fmac_f32_e32 v114, 0xba800000, v138
	v_mul_f32_e32 v108, v134, v134
	v_pk_add_f32 v[110:111], v[130:131], v[128:129]
	v_fmamk_f32 v115, v138, 0xba800000, v115
	v_pk_fma_f32 v[128:129], v[134:135], v[134:135], v[108:109] op_sel_hi:[1,1,0]
	v_mul_f32_e32 v108, v114, v114
	v_pk_add_f32 v[110:111], v[110:111], v[110:111] op_sel_hi:[0,1]
	v_pk_fma_f32 v[130:131], v[114:115], v[114:115], v[108:109] op_sel_hi:[1,1,0]
	v_fmamk_f32 v107, v138, 0xba800000, v107
	v_fmac_f32_e32 v106, 0xba800000, v138
	v_fmamk_f32 v147, v138, 0xba800000, v147
	v_fmac_f32_e32 v146, 0xba800000, v138
	v_mul_f32_e32 v128, v146, v146
	v_mul_f32_e32 v130, v147, v147
	v_mul_f32_e32 v108, v106, v106
	v_mul_f32_e32 v110, v107, v107
	v_pk_add_f32 v[128:129], v[128:129], v[130:131]
	v_pk_add_f32 v[108:109], v[108:109], v[110:111]
	v_pk_mov_b32 v[110:111], v[122:123], v[124:125] op_sel:[1,0]
	v_pk_add_f32 v[108:109], v[128:129], v[108:109]
	v_mov_b32_e32 v128, v122
	v_mov_b32_e32 v129, v125
	v_pk_add_f32 v[110:111], v[110:111], v[128:129]
	v_pk_mov_b32 v[128:129], v[116:117], v[118:119] op_sel:[1,0]
	v_mov_b32_e32 v130, v116
	v_mov_b32_e32 v131, v119
	v_pk_add_f32 v[128:129], v[128:129], v[130:131]
	v_add_f32_e32 v110, v110, v111
	v_pk_add_f32 v[128:129], v[128:129], v[128:129] op_sel:[0,1] op_sel_hi:[1,0]
	v_add_f32_e32 v110, 0, v110
	v_add_f32_e32 v130, v136, v137
	v_add_f32_e32 v138, v112, v113
	v_mov_b32_e32 v111, v144
	v_mov_b32_e32 v129, v145
	v_mov_b32_e32 v131, v104
	v_pk_add_f32 v[110:111], v[110:111], v[128:129]
	v_pk_add_f32 v[128:129], v[130:131], v[138:139]
	v_add_f32_e32 v108, v108, v109
	v_pk_add_f32 v[110:111], v[110:111], v[128:129]
	s_nop 0
	v_add_f32_dpp v108, v108, v108 quad_perm:[1,0,3,2] row_mask:0xf bank_mask:0xf bound_ctrl:1
	v_add_f32_e32 v110, v110, v111
	s_nop 0
	v_add_f32_dpp v108, v108, v108 quad_perm:[2,3,0,1] row_mask:0xf bank_mask:0xf bound_ctrl:1
	v_add_f32_dpp v110, v110, v110 quad_perm:[1,0,3,2] row_mask:0xf bank_mask:0xf bound_ctrl:1
	s_nop 0
	v_add_f32_dpp v108, v108, v108 row_half_mirror row_mask:0xf bank_mask:0xf bound_ctrl:1
	v_add_f32_dpp v110, v110, v110 quad_perm:[2,3,0,1] row_mask:0xf bank_mask:0xf bound_ctrl:1
	s_nop 0
	v_add_f32_dpp v108, v108, v108 row_mirror row_mask:0xf bank_mask:0xf bound_ctrl:1
	v_add_f32_dpp v110, v110, v110 row_half_mirror row_mask:0xf bank_mask:0xf bound_ctrl:1
	v_readlane_b32 s4, v108, 16
	v_readlane_b32 s9, v108, 48
	v_add_f32_dpp v110, v110, v110 row_mirror row_mask:0xf bank_mask:0xf bound_ctrl:1
	v_readlane_b32 s2, v108, 0
	v_readlane_b32 s3, v108, 32
	v_mov_b32_e32 v108, s4
	v_mov_b32_e32 v109, s9
	v_readlane_b32 s4, v110, 16
	v_readlane_b32 s9, v110, 48
	v_pk_add_f32 v[108:109], s[2:3], v[108:109]
	v_readlane_b32 s2, v110, 0
	v_readlane_b32 s3, v110, 32
	v_mov_b32_e32 v110, s4
	v_mov_b32_e32 v111, s9
	v_pk_add_f32 v[110:111], s[2:3], v[110:111]
	s_nop 0
	v_add_f32_e32 v140, v110, v111
	v_fmamk_f32 v123, v140, 0xba800000, v123
	v_fmac_f32_e32 v122, 0xba800000, v140
	v_fmamk_f32 v125, v140, 0xba800000, v125
	v_fmac_f32_e32 v124, 0xba800000, v140
	v_pk_mul_f32 v[110:111], v[124:125], v[124:125]
	v_pk_mul_f32 v[128:129], v[122:123], v[122:123]
	v_fmamk_f32 v117, v140, 0xba800000, v117
	v_pk_mov_b32 v[130:131], v[128:129], v[110:111] op_sel:[1,0]
	v_mov_b32_e32 v129, v111
	v_pk_add_f32 v[110:111], v[130:131], v[128:129]
	v_fmac_f32_e32 v116, 0xba800000, v140
	v_fmamk_f32 v119, v140, 0xba800000, v119
	v_fmac_f32_e32 v118, 0xba800000, v140
	v_pk_add_f32 v[110:111], v[110:111], v[110:111] op_sel_hi:[0,1]
	v_pk_mul_f32 v[128:129], v[118:119], v[118:119]
	v_pk_mul_f32 v[130:131], v[116:117], v[116:117]
	v_fmac_f32_e32 v136, 0xba800000, v140
	v_pk_mov_b32 v[138:139], v[130:131], v[128:129] op_sel:[1,0]
	v_mov_b32_e32 v131, v129
	v_fmamk_f32 v137, v140, 0xba800000, v137
	v_fmac_f32_e32 v112, 0xba800000, v140
	v_mul_f32_e32 v110, v136, v136
	v_pk_add_f32 v[128:129], v[138:139], v[130:131]
	v_fmamk_f32 v113, v140, 0xba800000, v113
	v_pk_fma_f32 v[130:131], v[136:137], v[136:137], v[110:111] op_sel_hi:[1,1,0]
	v_mul_f32_e32 v110, v112, v112
	v_pk_add_f32 v[128:129], v[128:129], v[128:129] op_sel_hi:[0,1]
	v_pk_fma_f32 v[138:139], v[112:113], v[112:113], v[110:111] op_sel_hi:[1,1,0]
	v_fmamk_f32 v105, v140, 0xba800000, v105
; #define GAS __attribute__((address_space(1)))
; #define LAS __attribute__((address_space(3)))
; __device__ __forceinline__ unsigned pk2(float lo, float hi) { typedef __bf16 bf2_t __attribute__((ext_vector_type(2))); const f32x2 v = {lo, hi}; return __builtin_bit_cast(unsigned, __builtin_convertvector(v, bf2_t)); }
; __device__ __forceinline__ unsigned dpp_swap1(unsigned v) { return (unsigned)__builtin_amdgcn_update_dpp(0, (int)v, 0xB1, 0xF, 0xF, true); }
; __device__ __forceinline__ void store_row_pk(bf16* rowp, int lane, const v2u (&o)[4]) {
;     const bool odd = (lane & 1) != 0; bf16* p = rowp + 4 * (lane & ~1) + (odd ? 256 : 0);
; #pragma unroll
;     for (int pr = 0; pr < 2; ++pr) { const v2u a = o[2 * pr], b = o[2 * pr + 1], send = odd ? a : b; v2u recv; recv.x = dpp_swap1(send.x); recv.y = dpp_swap1(send.y);
;         const v4u w = odd ? (v4u){recv.x, recv.y, b.x, b.y} : (v4u){a.x, a.y, recv.x, recv.y};
;         *(GAS v4u*)(p + 512 * pr) = w; }
; }
; __device__ __forceinline__ void p_r2(const Args& a, LAS unsigned char* lds, volatile LAS unsigned* MISC, int l, int wg, int G, int wave, int lane, int tid) {
;     ...
;             for (int r = 0; r < 2; ++r) ln_stats(x[r], mean[r], rstd[r]);
; #pragma unroll
;             for (int j = 0; j < 4; ++j) { const f32x4 g = *(const LAS f32x4*)(lds + R2_PAR + (1 * 256 + lane + 64 * j) * 16), bb = *(const LAS f32x4*)(lds + R2_PAR + (2 * 256 + lane + 64 * j) * 16);
; #pragma unroll
;                 for (int r = 0; r < 2; ++r) { x[r][j] = (x[r][j] - mean[r]) * rstd[r] * g + bb; ob[r][j].x = pk2(x[r][j][0], x[r][j][1]); ob[r][j].y = pk2(x[r][j][2], x[r][j][3]); } }
; #pragma unroll
;             for (int r = 0; r < 2; ++r) store_row_pk(X1 + (size_t)(t0 + r) * D, lane, ob[r]);
	v_fmac_f32_e32 v104, 0xba800000, v140
	v_fmamk_f32 v145, v140, 0xba800000, v145
	v_fmac_f32_e32 v144, 0xba800000, v140
	v_mul_f32_e32 v130, v144, v144
	v_mul_f32_e32 v138, v145, v145
	v_mul_f32_e32 v110, v104, v104
	v_mul_f32_e32 v128, v105, v105
	v_pk_add_f32 v[130:131], v[130:131], v[138:139]
	v_pk_add_f32 v[110:111], v[110:111], v[128:129]
	v_mov_b32_e32 v129, v108
	v_pk_add_f32 v[110:111], v[130:131], v[110:111]
	s_nop 0
	v_add_f32_e32 v110, v110, v111
	s_nop 1
	v_add_f32_dpp v110, v110, v110 quad_perm:[1,0,3,2] row_mask:0xf bank_mask:0xf bound_ctrl:1
	s_nop 1
	v_add_f32_dpp v110, v110, v110 quad_perm:[2,3,0,1] row_mask:0xf bank_mask:0xf bound_ctrl:1
	s_nop 1
	v_add_f32_dpp v110, v110, v110 row_half_mirror row_mask:0xf bank_mask:0xf bound_ctrl:1
	s_nop 1
	v_add_f32_dpp v110, v110, v110 row_mirror row_mask:0xf bank_mask:0xf bound_ctrl:1
	s_nop 0
	v_readlane_b32 s4, v110, 16
	v_readlane_b32 s9, v110, 48
	v_readlane_b32 s2, v110, 0
	v_readlane_b32 s3, v110, 32
	v_mov_b32_e32 v110, s4
	v_mov_b32_e32 v111, s9
	v_pk_add_f32 v[110:111], s[2:3], v[110:111]
	s_mov_b32 s2, 0x3727c5ac
	v_mov_b32_e32 v128, v110
	v_mov_b32_e32 v108, v111
	v_pk_add_f32 v[108:109], v[128:129], v[108:109]
	v_mov_b64_e32 v[142:143], s[2:3]
	v_pk_fma_f32 v[108:109], v[108:109], s[70:71], v[142:143] op_sel_hi:[1,0,0]
	s_ashr_i32 s9, s8, 31
	v_mul_f32_e32 v110, 0x4b800000, v109
	v_cmp_gt_f32_e64 s[54:55], s68, v109
	v_cmp_gt_f32_e32 vcc, s68, v108
	s_lshl_b64 s[2:3], s[8:9], 11
	v_cndmask_b32_e64 v109, v109, v110, s[54:55]
	v_rsq_f32_e32 v109, v109
	s_nop 0
	v_mul_f32_e32 v110, 0x45800000, v109
	v_cndmask_b32_e64 v188, v109, v110, s[54:55]
	v_mul_f32_e32 v109, 0x4b800000, v108
	v_cndmask_b32_e32 v108, v108, v109, vcc
	v_rsq_f32_e32 v108, v108
	v_pk_mul_f32 v[18:19], v[18:19], v[188:189] op_sel_hi:[1,0]
	v_pk_mul_f32 v[120:121], v[120:121], v[188:189] op_sel_hi:[1,0]
	v_mul_f32_e32 v109, 0x45800000, v108
	v_cndmask_b32_e32 v190, v108, v109, vcc
	ds_read_b128 v[108:111], v186 offset:4096
	ds_read_b128 v[148:151], v186 offset:8192
	s_waitcnt lgkmcnt(0)
	v_pk_fma_f32 v[138:139], v[120:121], v[110:111], v[150:151]
	v_pk_fma_f32 v[140:141], v[18:19], v[108:109], v[148:149]
	v_pk_mul_f32 v[18:19], v[122:123], v[190:191] op_sel_hi:[1,0]
	v_pk_mul_f32 v[120:121], v[124:125], v[190:191] op_sel_hi:[1,0]
	v_pk_fma_f32 v[130:131], v[108:109], v[18:19], v[148:149]
	v_pk_fma_f32 v[128:129], v[110:111], v[120:121], v[150:151]
	ds_read_b128 v[108:111], v186 offset:5120
	ds_read_b128 v[120:123], v186 offset:9216
	v_cvt_pk_bf16_f32 v189, v138, v139
	v_cvt_pk_bf16_f32 v191, v130, v131
	v_pk_mul_f32 v[18:19], v[126:127], v[188:189] op_sel_hi:[1,0]
	v_pk_mul_f32 v[124:125], v[132:133], v[188:189] op_sel_hi:[1,0]
	s_waitcnt lgkmcnt(0)
	v_pk_fma_f32 v[126:127], v[18:19], v[108:109], v[120:121]
	v_pk_mul_f32 v[18:19], v[116:117], v[190:191] op_sel_hi:[1,0]
	v_pk_mul_f32 v[116:117], v[118:119], v[190:191] op_sel_hi:[1,0]
	v_pk_fma_f32 v[124:125], v[124:125], v[110:111], v[122:123]
	v_pk_fma_f32 v[118:119], v[110:111], v[116:117], v[122:123]
	v_pk_fma_f32 v[120:121], v[108:109], v[18:19], v[120:121]
	ds_read_b128 v[108:111], v186 offset:6144
	ds_read_b128 v[148:151], v186 offset:10240
	v_pk_mul_f32 v[18:19], v[134:135], v[188:189] op_sel_hi:[1,0]
	v_pk_mul_f32 v[114:115], v[114:115], v[188:189] op_sel_hi:[1,0]
	v_pk_mul_f32 v[112:113], v[112:113], v[190:191] op_sel_hi:[1,0]
	v_cvt_pk_bf16_f32 v187, v140, v141
	s_waitcnt lgkmcnt(0)
	v_pk_fma_f32 v[116:117], v[18:19], v[108:109], v[148:149]
	v_pk_mul_f32 v[18:19], v[136:137], v[190:191] op_sel_hi:[1,0]
	v_pk_fma_f32 v[114:115], v[114:115], v[110:111], v[150:151]
	v_pk_fma_f32 v[110:111], v[110:111], v[112:113], v[150:151]
	v_pk_fma_f32 v[112:113], v[108:109], v[18:19], v[148:149]
	ds_read_b128 v[132:135], v186 offset:7168
	ds_read_b128 v[148:151], v186 offset:11264
	v_cvt_pk_bf16_f32 v193, v126, v127
	v_cvt_pk_bf16_f32 v194, v124, v125
	v_pk_mul_f32 v[18:19], v[146:147], v[188:189] op_sel_hi:[1,0]
	v_pk_mul_f32 v[122:123], v[144:145], v[190:191] op_sel_hi:[1,0]
	v_pk_mul_f32 v[106:107], v[106:107], v[188:189] op_sel_hi:[1,0]
	s_waitcnt lgkmcnt(0)
	v_pk_fma_f32 v[108:109], v[18:19], v[132:133], v[148:149]
	v_pk_mul_f32 v[18:19], v[104:105], v[190:191] op_sel_hi:[1,0]
	v_pk_fma_f32 v[104:105], v[132:133], v[122:123], v[148:149]
	v_cndmask_b32_e64 v132, v189, v194, s[44:45]
	v_cndmask_b32_e64 v133, v187, v193, s[44:45]
	v_pk_fma_f32 v[106:107], v[106:107], v[134:135], v[150:151]
	v_mov_b32_dpp v132, v132 quad_perm:[1,0,3,2] row_mask:0xf bank_mask:0xf bound_ctrl:1
	v_mov_b32_dpp v148, v133 quad_perm:[1,0,3,2] row_mask:0xf bank_mask:0xf bound_ctrl:1
	v_cvt_pk_bf16_f32 v197, v116, v117
	v_cvt_pk_bf16_f32 v202, v114, v115
	v_cvt_pk_bf16_f32 v146, v108, v109
	v_cvt_pk_bf16_f32 v147, v106, v107
	v_pk_fma_f32 v[18:19], v[134:135], v[18:19], v[150:151]
	v_lshl_add_u64 v[122:123], v[160:161], 0, s[2:3]
	v_cndmask_b32_e64 v135, v194, v132, s[44:45]
	v_cndmask_b32_e64 v134, v193, v148, s[44:45]
	v_cndmask_b32_e64 v133, v132, v189, s[44:45]
	v_cndmask_b32_e64 v132, v148, v187, s[44:45]
	global_store_dwordx4 v[122:123], v[132:135], off
	v_cvt_pk_bf16_f32 v192, v128, v129
	v_cvt_pk_bf16_f32 v195, v120, v121
	v_cndmask_b32_e64 v132, v202, v147, s[44:45]
	v_cndmask_b32_e64 v133, v197, v146, s[44:45]
	v_cvt_pk_bf16_f32 v196, v118, v119
	v_mov_b32_dpp v132, v132 quad_perm:[1,0,3,2] row_mask:0xf bank_mask:0xf bound_ctrl:1
	v_mov_b32_dpp v148, v133 quad_perm:[1,0,3,2] row_mask:0xf bank_mask:0xf bound_ctrl:1
	v_cndmask_b32_e64 v135, v147, v132, s[44:45]
	v_cndmask_b32_e64 v134, v146, v148, s[44:45]
	v_cndmask_b32_e64 v133, v132, v202, s[44:45]
	v_cndmask_b32_e64 v132, v148, v197, s[44:45]
; #define GAS __attribute__((address_space(1)))
; __device__ __forceinline__ unsigned pk2(float lo, float hi) { typedef __bf16 bf2_t __attribute__((ext_vector_type(2))); const f32x2 v = {lo, hi}; return __builtin_bit_cast(unsigned, __builtin_convertvector(v, bf2_t)); }
; __device__ __forceinline__ unsigned dpp_swap1(unsigned v) { return (unsigned)__builtin_amdgcn_update_dpp(0, (int)v, 0xB1, 0xF, 0xF, true); }
; __device__ __forceinline__ void store_row_pk(bf16* rowp, int lane, const v2u (&o)[4]) {
;     const bool odd = (lane & 1) != 0; bf16* p = rowp + 4 * (lane & ~1) + (odd ? 256 : 0);
; #pragma unroll
;     for (int pr = 0; pr < 2; ++pr) { const v2u a = o[2 * pr], b = o[2 * pr + 1], send = odd ? a : b; v2u recv; recv.x = dpp_swap1(send.x); recv.y = dpp_swap1(send.y);
;         const v4u w = odd ? (v4u){recv.x, recv.y, b.x, b.y} : (v4u){a.x, a.y, recv.x, recv.y};
;         *(GAS v4u*)(p + 512 * pr) = w; }
; }
; __device__ __forceinline__ void p_r2(const Args& a, LAS unsigned char* lds, volatile LAS unsigned* MISC, int l, int wg, int G, int wave, int lane, int tid) {
;     ...
;                 for (int r = 0; r < 2; ++r) { x[r][j] = (x[r][j] - mean[r]) * rstd[r] * g + bb; ob[r][j].x = pk2(x[r][j][0], x[r][j][1]); ob[r][j].y = pk2(x[r][j][2], x[r][j][3]); } }
; #pragma unroll
;             for (int r = 0; r < 2; ++r) store_row_pk(X1 + (size_t)(t0 + r) * D, lane, ob[r]);
; #pragma unroll
;             for (int r = 0; r < 2; ++r) ln_stats(x[r], mean[r], rstd[r]);
	s_add_i32 s2, s8, 1
	global_store_dwordx4 v[122:123], v[132:135], off offset:1024
	s_ashr_i32 s3, s2, 31
	s_lshl_b64 s[34:35], s[2:3], 11
	v_cndmask_b32_e64 v132, v192, v196, s[44:45]
	v_cndmask_b32_e64 v133, v191, v195, s[44:45]
	v_cvt_pk_bf16_f32 v136, v112, v113
	v_mov_b32_dpp v132, v132 quad_perm:[1,0,3,2] row_mask:0xf bank_mask:0xf bound_ctrl:1
	v_mov_b32_dpp v146, v133 quad_perm:[1,0,3,2] row_mask:0xf bank_mask:0xf bound_ctrl:1
	v_cvt_pk_bf16_f32 v137, v110, v111
	v_cvt_pk_bf16_f32 v144, v104, v105
	v_cvt_pk_bf16_f32 v145, v18, v19
	v_lshl_add_u64 v[122:123], v[160:161], 0, s[34:35]
	v_cndmask_b32_e64 v135, v196, v132, s[44:45]
	v_cndmask_b32_e64 v134, v195, v146, s[44:45]
	v_cndmask_b32_e64 v133, v132, v192, s[44:45]
	v_cndmask_b32_e64 v132, v146, v191, s[44:45]
	global_store_dwordx4 v[122:123], v[132:135], off
	s_lshl_b64 s[8:9], s[8:9], 10
	s_lshl_b64 s[2:3], s[2:3], 10
	v_cndmask_b32_e64 v132, v137, v145, s[44:45]
	v_cndmask_b32_e64 v133, v136, v144, s[44:45]
	s_nop 0
	v_mov_b32_dpp v132, v132 quad_perm:[1,0,3,2] row_mask:0xf bank_mask:0xf bound_ctrl:1
	v_mov_b32_dpp v146, v133 quad_perm:[1,0,3,2] row_mask:0xf bank_mask:0xf bound_ctrl:1
	v_cndmask_b32_e64 v135, v145, v132, s[44:45]
	v_cndmask_b32_e64 v134, v144, v146, s[44:45]
	v_cndmask_b32_e64 v133, v132, v137, s[44:45]
	v_cndmask_b32_e64 v132, v146, v136, s[44:45]
	global_store_dwordx4 v[122:123], v[132:135], off offset:1024
	v_pk_mov_b32 v[122:123], v[140:141], v[138:139] op_sel:[1,0]
	v_add_f32_e32 v136, v114, v115
	v_mov_b32_e32 v132, v140
	v_mov_b32_e32 v133, v139
	v_pk_add_f32 v[122:123], v[122:123], v[132:133]
	v_pk_mov_b32 v[132:133], v[126:127], v[124:125] op_sel:[1,0]
	v_mov_b32_e32 v134, v126
	v_mov_b32_e32 v135, v125
	v_pk_add_f32 v[132:133], v[132:133], v[134:135]
	v_add_f32_e32 v122, v122, v123
	v_pk_add_f32 v[132:133], v[132:133], v[132:133] op_sel:[0,1] op_sel_hi:[1,0]
	v_add_f32_e32 v122, 0, v122
	v_add_f32_e32 v134, v116, v117
	v_mov_b32_e32 v123, v108
	v_mov_b32_e32 v133, v109
	v_mov_b32_e32 v135, v106
	v_mov_b32_e32 v137, v107
	v_pk_add_f32 v[122:123], v[122:123], v[132:133]
	v_pk_add_f32 v[132:133], v[134:135], v[136:137]
	v_add_f32_e32 v145, v110, v111
	v_pk_add_f32 v[122:123], v[122:123], v[132:133]
	s_nop 0
	v_add_f32_e32 v122, v122, v123
	s_nop 1
	v_add_f32_dpp v122, v122, v122 quad_perm:[1,0,3,2] row_mask:0xf bank_mask:0xf bound_ctrl:1
	s_nop 1
	v_add_f32_dpp v122, v122, v122 quad_perm:[2,3,0,1] row_mask:0xf bank_mask:0xf bound_ctrl:1
	s_nop 1
	v_add_f32_dpp v122, v122, v122 row_half_mirror row_mask:0xf bank_mask:0xf bound_ctrl:1
	s_nop 1
	v_add_f32_dpp v122, v122, v122 row_mirror row_mask:0xf bank_mask:0xf bound_ctrl:1
	s_nop 0
	v_readlane_b32 s4, v122, 16
	v_readlane_b32 s25, v122, 48
	v_readlane_b32 s34, v122, 0
	v_readlane_b32 s35, v122, 32
	v_mov_b32_e32 v122, s4
	v_mov_b32_e32 v123, s25
	v_pk_add_f32 v[122:123], s[34:35], v[122:123]
	s_nop 0
	v_add_f32_e32 v144, v122, v123
	v_fmamk_f32 v141, v144, 0xba800000, v141
	v_fmac_f32_e32 v140, 0xba800000, v144
	v_fmamk_f32 v139, v144, 0xba800000, v139
	v_fmac_f32_e32 v138, 0xba800000, v144
	v_pk_mul_f32 v[122:123], v[138:139], v[138:139]
	v_pk_mul_f32 v[132:133], v[140:141], v[140:141]
	v_fmamk_f32 v127, v144, 0xba800000, v127
	v_pk_mov_b32 v[134:135], v[132:133], v[122:123] op_sel:[1,0]
	v_mov_b32_e32 v133, v123
	v_pk_add_f32 v[122:123], v[134:135], v[132:133]
	v_fmac_f32_e32 v126, 0xba800000, v144
	v_fmamk_f32 v125, v144, 0xba800000, v125
	v_fmac_f32_e32 v124, 0xba800000, v144
	v_pk_add_f32 v[122:123], v[122:123], v[122:123] op_sel_hi:[0,1]
	v_pk_mul_f32 v[132:133], v[124:125], v[124:125]
	v_pk_mul_f32 v[134:135], v[126:127], v[126:127]
	v_fmac_f32_e32 v116, 0xba800000, v144
	v_pk_mov_b32 v[136:137], v[134:135], v[132:133] op_sel:[1,0]
	v_mov_b32_e32 v135, v133
	v_fmamk_f32 v117, v144, 0xba800000, v117
	v_fmac_f32_e32 v114, 0xba800000, v144
	v_mul_f32_e32 v122, v116, v116
	v_pk_add_f32 v[132:133], v[136:137], v[134:135]
	v_fmamk_f32 v115, v144, 0xba800000, v115
	v_pk_fma_f32 v[134:135], v[116:117], v[116:117], v[122:123] op_sel_hi:[1,1,0]
	v_mul_f32_e32 v122, v114, v114
	v_pk_add_f32 v[132:133], v[132:133], v[132:133] op_sel_hi:[0,1]
	v_pk_fma_f32 v[136:137], v[114:115], v[114:115], v[122:123] op_sel_hi:[1,1,0]
	v_fmamk_f32 v107, v144, 0xba800000, v107
	v_fmac_f32_e32 v106, 0xba800000, v144
	v_fmamk_f32 v109, v144, 0xba800000, v109
	v_fmac_f32_e32 v108, 0xba800000, v144
	v_mul_f32_e32 v134, v108, v108
	v_mul_f32_e32 v136, v109, v109
	v_mul_f32_e32 v122, v106, v106
	v_mul_f32_e32 v132, v107, v107
	v_pk_add_f32 v[134:135], v[134:135], v[136:137]
	v_pk_add_f32 v[122:123], v[122:123], v[132:133]
	v_pk_mov_b32 v[132:133], v[130:131], v[128:129] op_sel:[1,0]
	v_pk_add_f32 v[122:123], v[134:135], v[122:123]
	v_mov_b32_e32 v134, v130
	v_mov_b32_e32 v135, v129
	v_pk_add_f32 v[132:133], v[132:133], v[134:135]
	v_pk_mov_b32 v[134:135], v[120:121], v[118:119] op_sel:[1,0]
	v_mov_b32_e32 v136, v120
	v_mov_b32_e32 v137, v119
	v_pk_add_f32 v[134:135], v[134:135], v[136:137]
	v_add_f32_e32 v132, v132, v133
	v_pk_add_f32 v[134:135], v[134:135], v[134:135] op_sel_hi:[0,1]
	v_add_f32_e32 v133, 0, v132
	v_add_f32_e32 v137, v112, v113
	v_mov_b32_e32 v136, v104
	v_mov_b32_e32 v144, v105
	v_mov_b32_e32 v134, v18
	v_mov_b32_e32 v132, v19
	v_pk_add_f32 v[136:137], v[136:137], v[144:145]
	v_pk_add_f32 v[132:133], v[134:135], v[132:133]
	v_add_f32_e32 v122, v122, v123
	v_pk_add_f32 v[132:133], v[136:137], v[132:133]
	s_nop 0
	v_add_f32_dpp v122, v122, v122 quad_perm:[1,0,3,2] row_mask:0xf bank_mask:0xf bound_ctrl:1
	v_add_f32_e32 v132, v132, v133
	s_nop 0
	v_add_f32_dpp v122, v122, v122 quad_perm:[2,3,0,1] row_mask:0xf bank_mask:0xf bound_ctrl:1
; #define LAS __attribute__((address_space(3)))
; __device__ __forceinline__ void ln_stats(const f32x4 (&v)[4], float& mean, float& rstd) {
;     float s = 0.f;
; #pragma unroll
;     for (int j = 0; j < 4; ++j) s += (v[j][0] + v[j][1]) + (v[j][2] + v[j][3]);
;     mean = wave_sum(s) * (1.f / D); float q = 0.f;
; #pragma unroll
;     for (int j = 0; j < 4; ++j) { const f32x4 d = v[j] - mean; q += (d[0] * d[0] + d[1] * d[1]) + (d[2] * d[2] + d[3] * d[3]); }
;     rstd = rsqrtf(wave_sum(q) * (1.f / D) + LN_EPS);
; }
; __device__ __forceinline__ void p_r2(const Args& a, LAS unsigned char* lds, volatile LAS unsigned* MISC, int l, int wg, int G, int wave, int lane, int tid) {
;     ...
;             for (int r = 0; r < 2; ++r) ln_stats(x[r], mean[r], rstd[r]);
; #pragma unroll
;             for (int j = 0; j < 4; ++j) { const f32x4 s1 = *(const LAS f32x4*)(lds + R2_PAR + (3 * 256 + lane + 64 * j) * 16), s0 = *(const LAS f32x4*)(lds + R2_PAR + (4 * 256 + lane + 64 * j) * 16);
; #pragma unroll
;                 for (int r = 0; r < 2; ++r) { u[r][j] = (x[r][j] - mean[r]) * rstd[r] * (1.0f + s1) + s0;
	v_add_f32_dpp v132, v132, v132 quad_perm:[1,0,3,2] row_mask:0xf bank_mask:0xf bound_ctrl:1
	s_nop 0
	v_add_f32_dpp v122, v122, v122 row_half_mirror row_mask:0xf bank_mask:0xf bound_ctrl:1
	v_add_f32_dpp v132, v132, v132 quad_perm:[2,3,0,1] row_mask:0xf bank_mask:0xf bound_ctrl:1
	s_nop 0
	v_add_f32_dpp v122, v122, v122 row_mirror row_mask:0xf bank_mask:0xf bound_ctrl:1
	v_add_f32_dpp v132, v132, v132 row_half_mirror row_mask:0xf bank_mask:0xf bound_ctrl:1
	v_readlane_b32 s4, v122, 16
	v_readlane_b32 s25, v122, 48
	v_add_f32_dpp v132, v132, v132 row_mirror row_mask:0xf bank_mask:0xf bound_ctrl:1
	v_readlane_b32 s34, v122, 0
	v_readlane_b32 s35, v122, 32
	v_mov_b32_e32 v122, s4
	v_mov_b32_e32 v123, s25
	v_readlane_b32 s4, v132, 16
	v_readlane_b32 s25, v132, 48
	v_pk_add_f32 v[122:123], s[34:35], v[122:123]
	v_readlane_b32 s34, v132, 0
	v_readlane_b32 s35, v132, 32
	v_mov_b32_e32 v132, s4
	v_mov_b32_e32 v133, s25
	v_pk_add_f32 v[132:133], s[34:35], v[132:133]
	s_nop 0
	v_add_f32_e32 v146, v132, v133
	v_fmamk_f32 v131, v146, 0xba800000, v131
	v_fmac_f32_e32 v130, 0xba800000, v146
	v_fmamk_f32 v129, v146, 0xba800000, v129
	v_fmac_f32_e32 v128, 0xba800000, v146
	v_pk_mul_f32 v[132:133], v[128:129], v[128:129]
	v_pk_mul_f32 v[134:135], v[130:131], v[130:131]
	v_fmamk_f32 v121, v146, 0xba800000, v121
	v_pk_mov_b32 v[136:137], v[134:135], v[132:133] op_sel:[1,0]
	v_mov_b32_e32 v135, v133
	v_pk_add_f32 v[132:133], v[136:137], v[134:135]
	v_fmac_f32_e32 v120, 0xba800000, v146
	v_fmamk_f32 v119, v146, 0xba800000, v119
	v_fmac_f32_e32 v118, 0xba800000, v146
	v_pk_add_f32 v[132:133], v[132:133], v[132:133] op_sel_hi:[0,1]
	v_pk_mul_f32 v[134:135], v[118:119], v[118:119]
	v_pk_mul_f32 v[136:137], v[120:121], v[120:121]
	v_fmac_f32_e32 v112, 0xba800000, v146
	v_pk_mov_b32 v[144:145], v[136:137], v[134:135] op_sel:[1,0]
	v_mov_b32_e32 v137, v135
	v_fmamk_f32 v113, v146, 0xba800000, v113
	v_fmac_f32_e32 v110, 0xba800000, v146
	v_mul_f32_e32 v132, v112, v112
	v_pk_add_f32 v[134:135], v[144:145], v[136:137]
	v_fmamk_f32 v111, v146, 0xba800000, v111
	v_pk_fma_f32 v[136:137], v[112:113], v[112:113], v[132:133] op_sel_hi:[1,1,0]
	v_mul_f32_e32 v132, v110, v110
	v_pk_add_f32 v[134:135], v[134:135], v[134:135] op_sel_hi:[0,1]
	v_pk_fma_f32 v[144:145], v[110:111], v[110:111], v[132:133] op_sel_hi:[1,1,0]
	v_fmamk_f32 v19, v146, 0xba800000, v19
	v_fmac_f32_e32 v18, 0xba800000, v146
	v_fmamk_f32 v105, v146, 0xba800000, v105
	v_fmac_f32_e32 v104, 0xba800000, v146
	v_mul_f32_e32 v136, v104, v104
	v_mul_f32_e32 v144, v105, v105
	v_mul_f32_e32 v132, v18, v18
	v_mul_f32_e32 v134, v19, v19
	v_pk_add_f32 v[136:137], v[136:137], v[144:145]
	v_pk_add_f32 v[132:133], v[132:133], v[134:135]
	v_mov_b32_e32 v135, v122
	v_pk_add_f32 v[132:133], v[136:137], v[132:133]
	s_nop 0
	v_add_f32_e32 v132, v132, v133
	s_nop 1
	v_add_f32_dpp v132, v132, v132 quad_perm:[1,0,3,2] row_mask:0xf bank_mask:0xf bound_ctrl:1
	s_nop 1
	v_add_f32_dpp v132, v132, v132 quad_perm:[2,3,0,1] row_mask:0xf bank_mask:0xf bound_ctrl:1
	s_nop 1
	v_add_f32_dpp v132, v132, v132 row_half_mirror row_mask:0xf bank_mask:0xf bound_ctrl:1
	s_nop 1
	v_add_f32_dpp v132, v132, v132 row_mirror row_mask:0xf bank_mask:0xf bound_ctrl:1
	s_nop 0
	v_readlane_b32 s4, v132, 16
	v_readlane_b32 s25, v132, 48
	v_readlane_b32 s34, v132, 0
	v_readlane_b32 s35, v132, 32
	v_mov_b32_e32 v132, s4
	v_mov_b32_e32 v133, s25
	v_pk_add_f32 v[132:133], s[34:35], v[132:133]
	s_nop 0
	v_mov_b32_e32 v134, v132
	v_mov_b32_e32 v122, v133
	v_pk_add_f32 v[122:123], v[134:135], v[122:123]
	s_nop 0
	v_pk_fma_f32 v[122:123], v[122:123], s[70:71], v[142:143] op_sel_hi:[1,0,0]
	ds_read_b128 v[134:137], v186 offset:12288
	ds_read_b128 v[142:145], v186 offset:16384
	v_mul_f32_e32 v132, 0x4b800000, v123
	v_cmp_gt_f32_e64 s[54:55], s68, v123
	v_cmp_gt_f32_e32 vcc, s68, v122
	s_waitcnt lgkmcnt(1)
	v_pk_add_f32 v[134:135], v[134:135], 1.0 op_sel_hi:[1,0]
	v_cndmask_b32_e64 v123, v123, v132, s[54:55]
	v_rsq_f32_e32 v123, v123
	v_pk_add_f32 v[136:137], v[136:137], 1.0 op_sel_hi:[1,0]
	v_mul_f32_e32 v132, 0x45800000, v123
	v_cndmask_b32_e64 v132, v123, v132, s[54:55]
	v_mul_f32_e32 v123, 0x4b800000, v122
	v_cndmask_b32_e32 v122, v122, v123, vcc
	v_rsq_f32_e32 v122, v122
	v_pk_mul_f32 v[140:141], v[140:141], v[132:133] op_sel_hi:[1,0]
	v_pk_mul_f32 v[138:139], v[138:139], v[132:133] op_sel_hi:[1,0]
	s_waitcnt lgkmcnt(0)
; __device__ __forceinline__ unsigned pk4_fp8(float a, float b, float c, float d) { int w = 0; w = __builtin_amdgcn_cvt_pk_fp8_f32(a, b, w, false); w = __builtin_amdgcn_cvt_pk_fp8_f32(c, d, w, true); return (unsigned)w; }
; #define LAS __attribute__((address_space(3)))
; __device__ __forceinline__ unsigned pk4_fp8(float a, float b, float c, float d) { int w = 0; w = __builtin_amdgcn_cvt_pk_fp8_f32(a, b, w, false); w = __builtin_amdgcn_cvt_pk_fp8_f32(c, d, w, true); return (unsigned)w; }
; __device__ __forceinline__ void p_r2(const Args& a, LAS unsigned char* lds, volatile LAS unsigned* MISC, int l, int wg, int G, int wave, int lane, int tid) {
;     ...
;             for (int j = 0; j < 4; ++j) { const f32x4 s1 = *(const LAS f32x4*)(lds + R2_PAR + (3 * 256 + lane + 64 * j) * 16), s0 = *(const LAS f32x4*)(lds + R2_PAR + (4 * 256 + lane + 64 * j) * 16);
; #pragma unroll
;                 for (int r = 0; r < 2; ++r) { u[r][j] = (x[r][j] - mean[r]) * rstd[r] * (1.0f + s1) + s0;
;                     uq[r][j] = pk4_fp8(u[r][j][0] * F8_SA1, u[r][j][1] * F8_SA1, u[r][j][2] * F8_SA1, u[r][j][3] * F8_SA1);
;                     const h16x2 h0 = __builtin_amdgcn_cvt_pkrtz(u[r][j][0], u[r][j][1]), h1 = __builtin_amdgcn_cvt_pkrtz(u[r][j][2], u[r][j][3]);
;                     const h16x2 l0 = __builtin_amdgcn_cvt_pkrtz(u[r][j][0] - (float)h0[0], u[r][j][1] - (float)h0[1]), l1 = __builtin_amdgcn_cvt_pkrtz(u[r][j][2] - (float)h1[0], u[r][j][3] - (float)h1[1]);
;                     const int row = 2 * wave + r, off = row * 2048 + ((((lane >> 1) + 32 * j) ^ (row & 15)) << 4) + 8 * (lane & 1);
;                     *(LAS v2u*)(lds + R2_UH + off) = (v2u){__builtin_bit_cast(unsigned, h0), __builtin_bit_cast(unsigned, h1)};
;                     *(LAS v2u*)(lds + R2_UL + off) = (v2u){__builtin_bit_cast(unsigned, l0), __builtin_bit_cast(unsigned, l1)}; } }
	v_pk_fma_f32 v[140:141], v[140:141], v[134:135], v[142:143]
	v_mul_f32_e32 v123, 0x45800000, v122
	v_cndmask_b32_e32 v122, v122, v123, vcc
	v_mul_f32_e32 v133, 4.0, v140
	v_mul_f32_e32 v146, 4.0, v141
	v_mov_b32_e32 v123, v16
	v_cvt_pk_fp8_f32 v123, v133, v146
	v_cvt_pkrtz_f16_f32 v146, v140, v141
	v_cvt_f32_f16_e32 v133, v146
	v_pk_fma_f32 v[138:139], v[138:139], v[136:137], v[144:145]
	v_sub_f32_e32 v133, v140, v133
	v_cvt_f32_f16_sdwa v140, v146 dst_sel:DWORD dst_unused:UNUSED_PAD src0_sel:WORD_1
	v_mul_f32_e32 v147, 4.0, v138
	v_mul_f32_e32 v148, 4.0, v139
	v_cvt_pk_fp8_f32 v123, v147, v148 op_sel:[0,0,1]
	v_cvt_pkrtz_f16_f32 v147, v138, v139
	v_sub_f32_e32 v140, v141, v140
	v_cvt_pkrtz_f16_f32 v140, v133, v140
	v_cvt_f32_f16_e32 v133, v147
	v_pk_mul_f32 v[130:131], v[130:131], v[122:123] op_sel_hi:[1,0]
	v_pk_mul_f32 v[128:129], v[128:129], v[122:123] op_sel_hi:[1,0]
	v_pk_fma_f32 v[130:131], v[134:135], v[130:131], v[142:143]
	v_sub_f32_e32 v133, v138, v133
	v_cvt_f32_f16_sdwa v138, v147 dst_sel:DWORD dst_unused:UNUSED_PAD src0_sel:WORD_1
	v_pk_fma_f32 v[136:137], v[136:137], v[128:129], v[144:145]
	v_mul_f32_e32 v129, 4.0, v130
	v_mov_b32_e32 v128, v16
	v_sub_f32_e32 v138, v139, v138
	v_cvt_pkrtz_f16_f32 v141, v133, v138
	v_mul_f32_e32 v133, 4.0, v131
	v_cvt_pk_fp8_f32 v128, v129, v133
	v_mul_f32_e32 v134, 4.0, v136
	v_mul_f32_e32 v135, 4.0, v137
	ds_write2st64_b64 v172, v[146:147], v[140:141] offset1:64
	v_cvt_pk_fp8_f32 v128, v134, v135 op_sel:[0,0,1]
	v_cvt_pkrtz_f16_f32 v134, v130, v131
	v_cvt_f32_f16_e32 v129, v134
	v_cvt_pkrtz_f16_f32 v135, v136, v137
	v_pk_mul_f32 v[126:127], v[126:127], v[132:133] op_sel_hi:[1,0]
	v_pk_mul_f32 v[124:125], v[124:125], v[132:133] op_sel_hi:[1,0]
	v_sub_f32_e32 v129, v130, v129
	v_cvt_f32_f16_sdwa v130, v134 dst_sel:DWORD dst_unused:UNUSED_PAD src0_sel:WORD_1
	v_pk_mul_f32 v[120:121], v[120:121], v[122:123] op_sel_hi:[1,0]
	v_pk_mul_f32 v[118:119], v[118:119], v[122:123] op_sel_hi:[1,0]
	v_pk_mul_f32 v[112:113], v[112:113], v[122:123] op_sel_hi:[1,0]
	v_sub_f32_e32 v130, v131, v130
	v_cvt_pkrtz_f16_f32 v130, v129, v130
	v_cvt_f32_f16_e32 v129, v135
	v_cvt_f32_f16_sdwa v131, v135 dst_sel:DWORD dst_unused:UNUSED_PAD src0_sel:WORD_1
	v_pk_mul_f32 v[110:111], v[110:111], v[122:123] op_sel_hi:[1,0]
	v_pk_mul_f32 v[104:105], v[104:105], v[122:123] op_sel_hi:[1,0]
	v_sub_f32_e32 v129, v136, v129
	v_sub_f32_e32 v131, v137, v131
	v_cvt_pkrtz_f16_f32 v131, v129, v131
	ds_write2st64_b64 v173, v[134:135], v[130:131] offset1:64
	ds_read_b128 v[134:137], v186 offset:13312
	ds_read_b128 v[138:141], v186 offset:17408
	v_pk_mul_f32 v[18:19], v[18:19], v[122:123] op_sel_hi:[1,0]
	s_waitcnt lgkmcnt(1)
	v_pk_add_f32 v[134:135], v[134:135], 1.0 op_sel_hi:[1,0]
	v_pk_add_f32 v[130:131], v[136:137], 1.0 op_sel_hi:[1,0]
	s_waitcnt lgkmcnt(0)
	v_pk_fma_f32 v[126:127], v[126:127], v[134:135], v[138:139]
	v_pk_fma_f32 v[136:137], v[124:125], v[130:131], v[140:141]
	v_mul_f32_e32 v125, 4.0, v126
	v_mul_f32_e32 v129, 4.0, v127
	v_mov_b32_e32 v124, v16
	v_cvt_pk_fp8_f32 v124, v125, v129
	v_mul_f32_e32 v133, 4.0, v136
	v_mul_f32_e32 v142, 4.0, v137
	v_cvt_pkrtz_f16_f32 v143, v136, v137
	v_cvt_pk_fp8_f32 v124, v133, v142 op_sel:[0,0,1]
	v_cvt_pkrtz_f16_f32 v142, v126, v127
	v_cvt_f32_f16_e32 v125, v142
	v_pk_fma_f32 v[120:121], v[134:135], v[120:121], v[138:139]
	v_pk_fma_f32 v[118:119], v[130:131], v[118:119], v[140:141]
	v_mov_b32_e32 v130, v16
	v_sub_f32_e32 v125, v126, v125
	v_cvt_f32_f16_sdwa v126, v142 dst_sel:DWORD dst_unused:UNUSED_PAD src0_sel:WORD_1
	v_mul_f32_e32 v129, 4.0, v119
	v_pk_mul_f32 v[116:117], v[116:117], v[132:133] op_sel_hi:[1,0]
	v_mov_b32_e32 v131, v16
	v_sub_f32_e32 v126, v127, v126
	v_cvt_pkrtz_f16_f32 v126, v125, v126
	v_cvt_f32_f16_e32 v125, v143
	v_cvt_f32_f16_sdwa v127, v143 dst_sel:DWORD dst_unused:UNUSED_PAD src0_sel:WORD_1
	v_pk_mul_f32 v[114:115], v[114:115], v[132:133] op_sel_hi:[1,0]
	v_pk_mul_f32 v[108:109], v[108:109], v[132:133] op_sel_hi:[1,0]
	v_sub_f32_e32 v125, v136, v125
	v_sub_f32_e32 v127, v137, v127
	v_cvt_pkrtz_f16_f32 v127, v125, v127
	ds_write2st64_b64 v174, v[142:143], v[126:127] offset1:64
	v_mul_f32_e32 v125, 4.0, v120
	v_mul_f32_e32 v126, 4.0, v121
	v_cvt_pk_fp8_f32 v130, v125, v126
	v_cvt_pkrtz_f16_f32 v126, v120, v121
	v_cvt_f32_f16_e32 v125, v126
	v_mul_f32_e32 v127, 4.0, v118
	v_cvt_pk_fp8_f32 v130, v127, v129 op_sel:[0,0,1]
	v_cvt_pkrtz_f16_f32 v127, v118, v119
	v_sub_f32_e32 v120, v120, v125
	v_cvt_f32_f16_sdwa v125, v126 dst_sel:DWORD dst_unused:UNUSED_PAD src0_sel:WORD_1
	v_pk_mul_f32 v[106:107], v[106:107], v[132:133] op_sel_hi:[1,0]
	v_sub_f32_e32 v121, v121, v125
	v_cvt_pkrtz_f16_f32 v120, v120, v121
	v_cvt_f32_f16_e32 v121, v127
	v_sub_f32_e32 v118, v118, v121
	v_cvt_f32_f16_sdwa v121, v127 dst_sel:DWORD dst_unused:UNUSED_PAD src0_sel:WORD_1
	v_sub_f32_e32 v119, v119, v121
	v_cvt_pkrtz_f16_f32 v121, v118, v119
	ds_write2st64_b64 v175, v[126:127], v[120:121] offset1:64
	ds_read_b128 v[118:121], v186 offset:14336
	ds_read_b128 v[134:137], v186 offset:18432
	s_waitcnt lgkmcnt(1)
	v_pk_add_f32 v[118:119], v[118:119], 1.0 op_sel_hi:[1,0]
	s_waitcnt lgkmcnt(0)
; #define GAS __attribute__((address_space(1)))
; #define LAS __attribute__((address_space(3)))
; __device__ __forceinline__ void store_row_q8(unsigned char* rowp, int lane, const unsigned (&d)[4]) {
;     const bool o1 = (lane & 1) != 0, o2 = (lane & 2) != 0;
;     unsigned p[2][2];
; #pragma unroll
;     for (int cc = 0; cc < 2; ++cc) { const unsigned keep = o1 ? d[2 * cc + 1] : d[2 * cc], send = o1 ? d[2 * cc] : d[2 * cc + 1], recv = dpp_swap1(send); p[cc][0] = o1 ? recv : keep; p[cc][1] = o1 ? keep : recv; }
;     const unsigned s0 = o2 ? p[0][0] : p[1][0], s1 = o2 ? p[0][1] : p[1][1], r0 = dpp_swap2(s0), r1 = dpp_swap2(s1);
;     const v4u w = o2 ? (v4u){r0, r1, p[1][0], p[1][1]} : (v4u){p[0][0], p[0][1], r0, r1};
;     *(GAS v4u*)(rowp + 16 * (lane >> 2) + 256 * (lane & 3)) = w;
; }
; __device__ __forceinline__ void p_r2(const Args& a, LAS unsigned char* lds, volatile LAS unsigned* MISC, int l, int wg, int G, int wave, int lane, int tid) {
;     ...
;             for (int j = 0; j < 4; ++j) { const f32x4 s1 = *(const LAS f32x4*)(lds + R2_PAR + (3 * 256 + lane + 64 * j) * 16), s0 = *(const LAS f32x4*)(lds + R2_PAR + (4 * 256 + lane + 64 * j) * 16);
; #pragma unroll
;                 for (int r = 0; r < 2; ++r) { u[r][j] = (x[r][j] - mean[r]) * rstd[r] * (1.0f + s1) + s0;
;                     uq[r][j] = pk4_fp8(u[r][j][0] * F8_SA1, u[r][j][1] * F8_SA1, u[r][j][2] * F8_SA1, u[r][j][3] * F8_SA1);
;                     const h16x2 h0 = __builtin_amdgcn_cvt_pkrtz(u[r][j][0], u[r][j][1]), h1 = __builtin_amdgcn_cvt_pkrtz(u[r][j][2], u[r][j][3]);
;                     const h16x2 l0 = __builtin_amdgcn_cvt_pkrtz(u[r][j][0] - (float)h0[0], u[r][j][1] - (float)h0[1]), l1 = __builtin_amdgcn_cvt_pkrtz(u[r][j][2] - (float)h1[0], u[r][j][3] - (float)h1[1]);
;                     const int row = 2 * wave + r, off = row * 2048 + ((((lane >> 1) + 32 * j) ^ (row & 15)) << 4) + 8 * (lane & 1);
;                     *(LAS v2u*)(lds + R2_UH + off) = (v2u){__builtin_bit_cast(unsigned, h0), __builtin_bit_cast(unsigned, h1)};
;                     *(LAS v2u*)(lds + R2_UL + off) = (v2u){__builtin_bit_cast(unsigned, l0), __builtin_bit_cast(unsigned, l1)}; } }
; #pragma unroll
;             for (int r = 0; r < 2; ++r) store_row_q8(U8 + (size_t)(t0 + r) * D, lane, uq[r]);
;             __syncthreads();
	v_pk_fma_f32 v[116:117], v[116:117], v[118:119], v[134:135]
	v_pk_add_f32 v[120:121], v[120:121], 1.0 op_sel_hi:[1,0]
	v_mul_f32_e32 v125, 4.0, v116
	v_mul_f32_e32 v126, 4.0, v117
	v_cvt_pk_fp8_f32 v131, v125, v126
	v_cvt_pkrtz_f16_f32 v126, v116, v117
	v_cvt_f32_f16_e32 v125, v126
	v_pk_fma_f32 v[114:115], v[114:115], v[120:121], v[136:137]
	v_pk_fma_f32 v[112:113], v[112:113], v[118:119], v[134:135]
	v_mul_f32_e32 v127, 4.0, v114
	v_sub_f32_e32 v116, v116, v125
	v_cvt_f32_f16_sdwa v125, v126 dst_sel:DWORD dst_unused:UNUSED_PAD src0_sel:WORD_1
	v_mul_f32_e32 v129, 4.0, v115
	v_cvt_pk_fp8_f32 v131, v127, v129 op_sel:[0,0,1]
	v_cvt_pkrtz_f16_f32 v127, v114, v115
	v_sub_f32_e32 v117, v117, v125
	v_cvt_pkrtz_f16_f32 v116, v116, v117
	v_cvt_f32_f16_e32 v117, v127
	v_pk_fma_f32 v[110:111], v[110:111], v[120:121], v[136:137]
	v_mov_b32_e32 v120, v16
	v_sub_f32_e32 v114, v114, v117
	v_cvt_f32_f16_sdwa v117, v127 dst_sel:DWORD dst_unused:UNUSED_PAD src0_sel:WORD_1
	v_sub_f32_e32 v115, v115, v117
	v_cvt_pkrtz_f16_f32 v117, v114, v115
	v_mul_f32_e32 v114, 4.0, v112
	v_mul_f32_e32 v115, 4.0, v113
	v_cvt_pk_fp8_f32 v120, v114, v115
	ds_write2st64_b64 v176, v[126:127], v[116:117] offset1:64
	v_mul_f32_e32 v116, 4.0, v110
	v_mul_f32_e32 v117, 4.0, v111
	v_cvt_pkrtz_f16_f32 v114, v112, v113
	v_cvt_pk_fp8_f32 v120, v116, v117 op_sel:[0,0,1]
	v_cvt_f32_f16_e32 v116, v114
	v_cvt_pkrtz_f16_f32 v115, v110, v111
	v_mov_b32_e32 v126, v16
	v_sub_f32_e32 v112, v112, v116
	v_cvt_f32_f16_sdwa v116, v114 dst_sel:DWORD dst_unused:UNUSED_PAD src0_sel:WORD_1
	v_sub_f32_e32 v113, v113, v116
	v_cvt_pkrtz_f16_f32 v112, v112, v113
	v_cvt_f32_f16_e32 v113, v115
	v_sub_f32_e32 v110, v110, v113
	v_cvt_f32_f16_sdwa v113, v115 dst_sel:DWORD dst_unused:UNUSED_PAD src0_sel:WORD_1
	v_sub_f32_e32 v111, v111, v113
	v_cvt_pkrtz_f16_f32 v113, v110, v111
	ds_write2st64_b64 v177, v[114:115], v[112:113] offset1:64
	ds_read_b128 v[110:113], v186 offset:15360
	ds_read_b128 v[114:117], v186 offset:19456
	s_waitcnt lgkmcnt(1)
	v_pk_add_f32 v[110:111], v[110:111], 1.0 op_sel_hi:[1,0]
	s_waitcnt lgkmcnt(0)
	v_pk_fma_f32 v[108:109], v[108:109], v[110:111], v[114:115]
	v_pk_add_f32 v[112:113], v[112:113], 1.0 op_sel_hi:[1,0]
	v_mul_f32_e32 v118, 4.0, v108
	v_mul_f32_e32 v119, 4.0, v109
	v_cvt_pk_fp8_f32 v126, v118, v119
	v_pk_fma_f32 v[106:107], v[106:107], v[112:113], v[116:117]
	v_cvt_pkrtz_f16_f32 v118, v108, v109
	v_mul_f32_e32 v121, 4.0, v106
	v_mul_f32_e32 v125, 4.0, v107
	v_cvt_pk_fp8_f32 v126, v121, v125 op_sel:[0,0,1]
	v_cvt_f32_f16_e32 v121, v118
	v_cvt_pkrtz_f16_f32 v119, v106, v107
	v_pk_fma_f32 v[104:105], v[104:105], v[110:111], v[114:115]
	v_mov_b32_e32 v110, v16
	v_sub_f32_e32 v108, v108, v121
	v_cvt_f32_f16_sdwa v121, v118 dst_sel:DWORD dst_unused:UNUSED_PAD src0_sel:WORD_1
	v_pk_fma_f32 v[18:19], v[18:19], v[112:113], v[116:117]
	v_sub_f32_e32 v109, v109, v121
	v_cvt_pkrtz_f16_f32 v108, v108, v109
	v_cvt_f32_f16_e32 v109, v119
	v_sub_f32_e32 v106, v106, v109
	v_cvt_f32_f16_sdwa v109, v119 dst_sel:DWORD dst_unused:UNUSED_PAD src0_sel:WORD_1
	v_sub_f32_e32 v107, v107, v109
	v_cvt_pkrtz_f16_f32 v109, v106, v107
	v_mul_f32_e32 v106, 4.0, v104
	v_mul_f32_e32 v107, 4.0, v105
	v_cvt_pk_fp8_f32 v110, v106, v107
	ds_write2st64_b64 v178, v[118:119], v[108:109] offset1:64
	v_mul_f32_e32 v108, 4.0, v18
	v_mul_f32_e32 v109, 4.0, v19
	v_cvt_pkrtz_f16_f32 v106, v104, v105
	v_cvt_pk_fp8_f32 v110, v108, v109 op_sel:[0,0,1]
	v_cvt_f32_f16_e32 v108, v106
	v_cvt_pkrtz_f16_f32 v107, v18, v19
	v_sub_f32_e32 v104, v104, v108
	v_cvt_f32_f16_sdwa v108, v106 dst_sel:DWORD dst_unused:UNUSED_PAD src0_sel:WORD_1
	v_sub_f32_e32 v105, v105, v108
	v_cvt_pkrtz_f16_f32 v104, v104, v105
	v_cvt_f32_f16_e32 v105, v107
	v_sub_f32_e32 v18, v18, v105
	v_cvt_f32_f16_sdwa v105, v107 dst_sel:DWORD dst_unused:UNUSED_PAD src0_sel:WORD_1
	v_sub_f32_e32 v19, v19, v105
	v_cvt_pkrtz_f16_f32 v105, v18, v19
	ds_write2st64_b64 v179, v[106:107], v[104:105] offset1:64
	v_cndmask_b32_e64 v18, v123, v124, s[44:45]
	v_cndmask_b32_e64 v104, v131, v126, s[44:45]
	s_nop 0
	v_mov_b32_dpp v18, v18 quad_perm:[1,0,3,2] row_mask:0xf bank_mask:0xf bound_ctrl:1
	v_mov_b32_dpp v104, v104 quad_perm:[1,0,3,2] row_mask:0xf bank_mask:0xf bound_ctrl:1
	v_cndmask_b32_e64 v19, v18, v123, s[44:45]
	v_cndmask_b32_e64 v18, v124, v18, s[44:45]
	v_cndmask_b32_e64 v105, v104, v131, s[44:45]
	v_cndmask_b32_e64 v104, v126, v104, s[44:45]
	v_cndmask_b32_e64 v106, v19, v105, s[46:47]
	v_cndmask_b32_e64 v107, v18, v104, s[46:47]
	s_nop 0
	v_mov_b32_dpp v108, v106 quad_perm:[2,3,0,1] row_mask:0xf bank_mask:0xf bound_ctrl:1
	v_mov_b32_dpp v109, v107 quad_perm:[2,3,0,1] row_mask:0xf bank_mask:0xf bound_ctrl:1
	v_cndmask_b32_e64 v107, v104, v109, s[46:47]
	v_cndmask_b32_e64 v106, v105, v108, s[46:47]
	v_cndmask_b32_e64 v105, v109, v18, s[46:47]
	v_cndmask_b32_e64 v104, v108, v19, s[46:47]
	v_lshl_add_u64 v[18:19], v[164:165], 0, s[8:9]
	global_store_dwordx4 v[18:19], v[104:107], off
	v_cndmask_b32_e64 v18, v128, v130, s[44:45]
	s_nop 0
	v_cndmask_b32_e64 v104, v120, v110, s[44:45]
	v_mov_b32_dpp v18, v18 quad_perm:[1,0,3,2] row_mask:0xf bank_mask:0xf bound_ctrl:1
	v_cndmask_b32_e64 v19, v18, v128, s[44:45]
	v_mov_b32_dpp v104, v104 quad_perm:[1,0,3,2] row_mask:0xf bank_mask:0xf bound_ctrl:1
	v_cndmask_b32_e64 v18, v130, v18, s[44:45]
	v_cndmask_b32_e64 v105, v104, v120, s[44:45]
	v_cndmask_b32_e64 v104, v110, v104, s[44:45]
	v_cndmask_b32_e64 v106, v19, v105, s[46:47]
	v_cndmask_b32_e64 v107, v18, v104, s[46:47]
	s_nop 0
	v_mov_b32_dpp v108, v106 quad_perm:[2,3,0,1] row_mask:0xf bank_mask:0xf bound_ctrl:1
	v_mov_b32_dpp v109, v107 quad_perm:[2,3,0,1] row_mask:0xf bank_mask:0xf bound_ctrl:1
	v_cndmask_b32_e64 v107, v104, v109, s[46:47]
	v_cndmask_b32_e64 v106, v105, v108, s[46:47]
	v_cndmask_b32_e64 v105, v109, v18, s[46:47]
	v_cndmask_b32_e64 v104, v108, v19, s[46:47]
	v_lshl_add_u64 v[18:19], v[164:165], 0, s[2:3]
	global_store_dwordx4 v[18:19], v[104:107], off
	ds_read2st64_b32 v[144:145], v65 offset1:8
	ds_read2st64_b32 v[146:147], v65 offset0:16 offset1:24
	ds_read2st64_b32 v[148:149], v65 offset0:32 offset1:40
	ds_read2st64_b32 v[150:151], v65 offset0:48 offset1:56
	s_waitcnt lgkmcnt(0)
	s_barrier
; #define LAS __attribute__((address_space(3)))
; __device__ __forceinline__ void p_r2(const Args& a, LAS unsigned char* lds, volatile LAS unsigned* MISC, int l, int wg, int G, int wave, int lane, int tid) {
;     ...
;             f32x4 acc[2] = {(f32x4){0.f, 0.f, 0.f, 0.f}, (f32x4){0.f, 0.f, 0.f, 0.f}};
; #pragma unroll
;             for (int s = 0; s < 4; ++s) { const int off = fr * 2048 + (((4 * (4 * wave + s) + fq) ^ fr) << 4);
;                 const f16x8 ah = *(const LAS f16x8*)(lds + R2_UH + off), al = *(const LAS f16x8*)(lds + R2_UL + off);
; #pragma unroll
;                 for (int nt = 0; nt < 2; ++nt) { acc[nt] = __builtin_amdgcn_mfma_f32_16x16x32_f16(ah, bh[s][nt], acc[nt], 0, 0, 0); acc[nt] = __builtin_amdgcn_mfma_f32_16x16x32_f16(ah, bl[s][nt], acc[nt], 0, 0, 0);
;                     acc[nt] = __builtin_amdgcn_mfma_f32_16x16x32_f16(al, bh[s][nt], acc[nt], 0, 0, 0); } }
; #pragma unroll
;             for (int nt = 0; nt < 2; ++nt)
; #pragma unroll
;                 for (int r = 0; r < 4; ++r) PART[(wave * 16 + 4 * fq + r) * 32 + 16 * nt + fr] = acc[nt][r];
;             __syncthreads();
;             float sgm = rbias;
; #pragma unroll
;             for (int w = 0; w < 8; ++w) sgm += PART[(w * 16 + (tid >> 5)) * 32 + (tid & 31)];
;             { const int half = lane >> 5, ee = lane & 31; float lg = sgm;
;               int si[4]; float sv[4];
; #pragma unroll
;               for (int k = 0; k < 4; ++k) { float mx = row16_max(lg); mx = fmaxf(mx, __shfl_xor(mx, 16)); const unsigned long long bal = __ballot(lg == mx);
;                   const unsigned bits = half ? (unsigned)(bal >> 32) : (unsigned)bal; si[k] = __ffs((int)bits) - 1; sv[k] = mx; if (ee == si[k]) lg = -3.0e38f; }
;               const float e1 = ex2((sv[1] - sv[0]) * LOG2E), e2 = ex2((sv[2] - sv[0]) * LOG2E), e3 = ex2((sv[3] - sv[0]) * LOG2E), inv = 1.0f / (1.0f + e1 + e2 + e3);
;               if (ee == 0) { const int t = tb + 2 * wave + half;
;                   *(LAS v4i*)(lds + R2_TOP + (t - 256 * chunk) * 16) = (v4i){si[0], si[1], si[2], si[3]}; *(LAS f32x4*)(lds + R2_TOP + 4096 + (t - 256 * chunk) * 16) = (f32x4){inv, e1 * inv, e2 * inv, e3 * inv};
; #pragma unroll
;                   for (int k = 0; k < 4; ++k) __hip_atomic_fetch_add((LAS unsigned*)(MISC + MW_HIST + si[k]), 1u, __ATOMIC_RELAXED, __HIP_MEMORY_SCOPE_WORKGROUP); } }
	s_cmp_eq_u32 s37, 0
	s_cbranch_scc1 .Lr2_first
	ds_read_b128 v[104:107], v180
	ds_read_b128 v[108:111], v180 offset:32768
	ds_read_b128 v[120:123], v181
	ds_read_b128 v[124:127], v181 offset:32768
	v_add_f32_e32 v128, v167, v144
	v_add_f32_e32 v128, v128, v145
	v_add_f32_e32 v128, v128, v146
	v_add_f32_e32 v128, v128, v147
	v_add_f32_e32 v128, v128, v148
	v_add_f32_e32 v128, v128, v149
	v_add_f32_e32 v128, v128, v150
	v_add_f32_e32 v128, v128, v151
	s_nop 1
	v_max_f32_dpp v129, v128, v128 quad_perm:[1,0,3,2] row_mask:0xf bank_mask:0xf bound_ctrl:1
	s_nop 1
	v_max_f32_dpp v129, v129, v129 quad_perm:[2,3,0,1] row_mask:0xf bank_mask:0xf bound_ctrl:1
	s_nop 1
	v_max_f32_dpp v129, v129, v129 row_half_mirror row_mask:0xf bank_mask:0xf bound_ctrl:1
	s_nop 1
	v_max_f32_dpp v129, v129, v129 row_mirror row_mask:0xf bank_mask:0xf bound_ctrl:1
	v_mov_b32_e32 v142, v129
	s_nop 1
	v_permlane16_swap_b32_e32 v142, v129
	v_max_f32_e32 v129, v129, v142
	v_cmp_eq_f32_e32 vcc, v128, v129
	s_nop 1
	v_lshrrev_b64 v[140:141], v166, vcc
	v_ffbl_b32_e32 v136, v140
	v_cmp_ne_u32_e32 vcc, v67, v136
	s_nop 1
	v_cndmask_b32_e32 v130, v233, v128, vcc
	s_waitcnt lgkmcnt(3)
	v_mfma_f32_16x16x32_f16 v[112:115], v[104:107], v[0:3], 0
	v_mfma_f32_16x16x32_f16 v[116:119], v[104:107], v[8:11], 0
	v_mfma_f32_16x16x32_f16 v[112:115], v[104:107], v[4:7], v[112:115]
	v_mfma_f32_16x16x32_f16 v[116:119], v[104:107], v[12:15], v[116:119]
	s_waitcnt lgkmcnt(2)
	v_mfma_f32_16x16x32_f16 v[112:115], v[108:111], v[0:3], v[112:115]
	v_mfma_f32_16x16x32_f16 v[116:119], v[108:111], v[8:11], v[116:119]
	ds_read_b128 v[104:107], v182
	ds_read_b128 v[108:111], v182 offset:32768
	s_nop 1
	v_max_f32_dpp v131, v130, v130 quad_perm:[1,0,3,2] row_mask:0xf bank_mask:0xf bound_ctrl:1
	s_nop 1
	v_max_f32_dpp v131, v131, v131 quad_perm:[2,3,0,1] row_mask:0xf bank_mask:0xf bound_ctrl:1
	s_nop 1
	v_max_f32_dpp v131, v131, v131 row_half_mirror row_mask:0xf bank_mask:0xf bound_ctrl:1
	s_nop 1
	v_max_f32_dpp v131, v131, v131 row_mirror row_mask:0xf bank_mask:0xf bound_ctrl:1
	v_mov_b32_e32 v142, v131
	s_nop 1
	v_permlane16_swap_b32_e32 v142, v131
	v_max_f32_e32 v131, v131, v142
	v_cmp_eq_f32_e32 vcc, v130, v131
	s_nop 1
	v_lshrrev_b64 v[140:141], v166, vcc
	v_ffbl_b32_e32 v137, v140
	v_cmp_ne_u32_e32 vcc, v67, v137
	s_nop 1
	v_cndmask_b32_e32 v132, v233, v130, vcc
	s_waitcnt lgkmcnt(3)
	v_mfma_f32_16x16x32_f16 v[112:115], v[120:123], v[20:23], v[112:115]
	v_mfma_f32_16x16x32_f16 v[116:119], v[120:123], v[28:31], v[116:119]
	v_mfma_f32_16x16x32_f16 v[112:115], v[120:123], v[24:27], v[112:115]
	v_mfma_f32_16x16x32_f16 v[116:119], v[120:123], v[32:35], v[116:119]
	s_waitcnt lgkmcnt(2)
	v_mfma_f32_16x16x32_f16 v[112:115], v[124:127], v[20:23], v[112:115]
	v_mfma_f32_16x16x32_f16 v[116:119], v[124:127], v[28:31], v[116:119]
	ds_read_b128 v[120:123], v183
	ds_read_b128 v[124:127], v183 offset:32768
	s_nop 1
	v_max_f32_dpp v133, v132, v132 quad_perm:[1,0,3,2] row_mask:0xf bank_mask:0xf bound_ctrl:1
	s_nop 1
	v_max_f32_dpp v133, v133, v133 quad_perm:[2,3,0,1] row_mask:0xf bank_mask:0xf bound_ctrl:1
	s_nop 1
	v_max_f32_dpp v133, v133, v133 row_half_mirror row_mask:0xf bank_mask:0xf bound_ctrl:1
	s_nop 1
	v_max_f32_dpp v133, v133, v133 row_mirror row_mask:0xf bank_mask:0xf bound_ctrl:1
	v_mov_b32_e32 v142, v133
	s_nop 1
	v_permlane16_swap_b32_e32 v142, v133
	v_max_f32_e32 v133, v133, v142
	v_cmp_eq_f32_e32 vcc, v132, v133
	s_nop 1
	v_lshrrev_b64 v[140:141], v166, vcc
	v_ffbl_b32_e32 v138, v140
	v_cmp_ne_u32_e32 vcc, v67, v138
	s_nop 1
	v_cndmask_b32_e32 v134, v233, v132, vcc
	s_waitcnt lgkmcnt(3)
	v_mfma_f32_16x16x32_f16 v[112:115], v[104:107], v[36:39], v[112:115]
	v_mfma_f32_16x16x32_f16 v[116:119], v[104:107], v[44:47], v[116:119]
	v_mfma_f32_16x16x32_f16 v[112:115], v[104:107], v[40:43], v[112:115]
	v_mfma_f32_16x16x32_f16 v[116:119], v[104:107], v[48:51], v[116:119]
	s_waitcnt lgkmcnt(2)
	v_mfma_f32_16x16x32_f16 v[112:115], v[108:111], v[36:39], v[112:115]
	v_mfma_f32_16x16x32_f16 v[116:119], v[108:111], v[44:47], v[116:119]
	s_nop 1
	v_max_f32_dpp v135, v134, v134 quad_perm:[1,0,3,2] row_mask:0xf bank_mask:0xf bound_ctrl:1
	s_nop 1
	v_max_f32_dpp v135, v135, v135 quad_perm:[2,3,0,1] row_mask:0xf bank_mask:0xf bound_ctrl:1
	s_nop 1
	v_max_f32_dpp v135, v135, v135 row_half_mirror row_mask:0xf bank_mask:0xf bound_ctrl:1
	s_nop 1
	v_max_f32_dpp v135, v135, v135 row_mirror row_mask:0xf bank_mask:0xf bound_ctrl:1
	v_mov_b32_e32 v142, v135
	s_nop 1
	v_permlane16_swap_b32_e32 v142, v135
	v_max_f32_e32 v135, v135, v142
	v_cmp_eq_f32_e32 vcc, v134, v135
	s_waitcnt lgkmcnt(1)
	v_mfma_f32_16x16x32_f16 v[112:115], v[120:123], v[52:55], v[112:115]
	v_mfma_f32_16x16x32_f16 v[116:119], v[120:123], v[60:63], v[116:119]
	v_mfma_f32_16x16x32_f16 v[112:115], v[120:123], v[56:59], v[112:115]
	v_mfma_f32_16x16x32_f16 v[116:119], v[120:123], v[68:71], v[116:119]
	s_waitcnt lgkmcnt(0)
	v_mfma_f32_16x16x32_f16 v[112:115], v[124:127], v[52:55], v[112:115]
	v_mfma_f32_16x16x32_f16 v[116:119], v[124:127], v[60:63], v[116:119]
	s_and_saveexec_b64 s[2:3], s[48:49]
	s_cbranch_execz .Lr2_tail_done
	v_sub_f32_e32 v135, v135, v129
	v_sub_f32_e32 v133, v133, v129
	v_sub_f32_e32 v131, v131, v129
	v_lshrrev_b64 v[140:141], v166, vcc
	v_mul_f32_e32 v131, 0x3fb8aa3b, v131
	v_ffbl_b32_e32 v139, v140
	v_mul_f32_e32 v133, 0x3fb8aa3b, v133
	v_exp_f32_e32 v144, v131
	v_mul_f32_e32 v135, 0x3fb8aa3b, v135
	v_exp_f32_e32 v145, v133
	v_exp_f32_e32 v135, v135
	v_add_f32_e32 v146, 1.0, v144
	v_add_f32_e32 v146, v146, v145
	v_add_f32_e32 v146, v146, v135
	v_div_scale_f32 v147, s[8:9], v146, v146, 1.0
	v_rcp_f32_e32 v148, v147
	s_nop 0
	v_fma_f32 v149, -v147, v148, 1.0
	v_fmac_f32_e32 v148, v149, v148
	v_div_scale_f32 v149, vcc, 1.0, v146, 1.0
	v_mul_f32_e32 v150, v149, v148
	v_fma_f32 v151, -v147, v150, v149
	v_fmac_f32_e32 v150, v151, v148
	v_fma_f32 v147, -v147, v150, v149
	v_div_fmas_f32 v147, v147, v148, v150
	v_div_fixup_f32 v148, v147, v146, 1.0
	v_add_u32_e32 v140, 0xffffef00, v185
	ds_write_b128 v140, v[136:139]
	v_mul_f32_e32 v149, v144, v148
	v_mul_f32_e32 v150, v145, v148
	v_mul_f32_e32 v151, v135, v148
	v_add_u32_e32 v141, 0xffffff00, v185
	ds_write_b128 v141, v[148:151]
	v_lshl_add_u32 v140, v136, 2, s26
	ds_add_u32 v140, v201
	v_lshl_add_u32 v140, v137, 2, s26
	ds_add_u32 v140, v201
	v_lshl_add_u32 v140, v138, 2, s26
	ds_add_u32 v140, v201
	v_lshl_add_u32 v140, v139, 2, s26
	ds_add_u32 v140, v201

; #define LAS __attribute__((address_space(3)))
; __device__ __forceinline__ void p_r2(const Args& a, LAS unsigned char* lds, volatile LAS unsigned* MISC, int l, int wg, int G, int wave, int lane, int tid) {
;     ...
;             f32x4 acc[2] = {(f32x4){0.f, 0.f, 0.f, 0.f}, (f32x4){0.f, 0.f, 0.f, 0.f}};
; #pragma unroll
;             for (int s = 0; s < 4; ++s) { const int off = fr * 2048 + (((4 * (4 * wave + s) + fq) ^ fr) << 4);
;                 const f16x8 ah = *(const LAS f16x8*)(lds + R2_UH + off), al = *(const LAS f16x8*)(lds + R2_UL + off);
; #pragma unroll
;                 for (int nt = 0; nt < 2; ++nt) { acc[nt] = __builtin_amdgcn_mfma_f32_16x16x32_f16(ah, bh[s][nt], acc[nt], 0, 0, 0); acc[nt] = __builtin_amdgcn_mfma_f32_16x16x32_f16(ah, bl[s][nt], acc[nt], 0, 0, 0);
;                     acc[nt] = __builtin_amdgcn_mfma_f32_16x16x32_f16(al, bh[s][nt], acc[nt], 0, 0, 0); } }
; #pragma unroll
;             for (int nt = 0; nt < 2; ++nt)
; #pragma unroll
;                 for (int r = 0; r < 4; ++r) PART[(wave * 16 + 4 * fq + r) * 32 + 16 * nt + fr] = acc[nt][r];
;             __syncthreads();
.Lr2_part:
	s_nop 7
	ds_write2_b32 v184, v112, v116 offset1:16
	ds_write2_b32 v184, v113, v117 offset0:32 offset1:48
	ds_write2_b32 v184, v114, v118 offset0:64 offset1:80
	ds_write2_b32 v184, v115, v119 offset0:96 offset1:112
	s_waitcnt lgkmcnt(0)
	s_barrier
	s_branch .LBB0_823
.Lr2_first:
	ds_read_b128 v[104:107], v180
	ds_read_b128 v[108:111], v180 offset:32768
	ds_read_b128 v[120:123], v181
	ds_read_b128 v[124:127], v181 offset:32768
	s_waitcnt lgkmcnt(3)
	v_mfma_f32_16x16x32_f16 v[112:115], v[104:107], v[0:3], 0
	v_mfma_f32_16x16x32_f16 v[116:119], v[104:107], v[8:11], 0
	v_mfma_f32_16x16x32_f16 v[112:115], v[104:107], v[4:7], v[112:115]
	v_mfma_f32_16x16x32_f16 v[116:119], v[104:107], v[12:15], v[116:119]
	s_waitcnt lgkmcnt(2)
	v_mfma_f32_16x16x32_f16 v[112:115], v[108:111], v[0:3], v[112:115]
	v_mfma_f32_16x16x32_f16 v[116:119], v[108:111], v[8:11], v[116:119]
	ds_read_b128 v[104:107], v182
	ds_read_b128 v[108:111], v182 offset:32768
	s_waitcnt lgkmcnt(3)
	v_mfma_f32_16x16x32_f16 v[112:115], v[120:123], v[20:23], v[112:115]
	v_mfma_f32_16x16x32_f16 v[116:119], v[120:123], v[28:31], v[116:119]
	v_mfma_f32_16x16x32_f16 v[112:115], v[120:123], v[24:27], v[112:115]
	v_mfma_f32_16x16x32_f16 v[116:119], v[120:123], v[32:35], v[116:119]
	s_waitcnt lgkmcnt(2)
	v_mfma_f32_16x16x32_f16 v[112:115], v[124:127], v[20:23], v[112:115]
	v_mfma_f32_16x16x32_f16 v[116:119], v[124:127], v[28:31], v[116:119]
	ds_read_b128 v[120:123], v183
	ds_read_b128 v[124:127], v183 offset:32768
	s_waitcnt lgkmcnt(3)
	v_mfma_f32_16x16x32_f16 v[112:115], v[104:107], v[36:39], v[112:115]
	v_mfma_f32_16x16x32_f16 v[116:119], v[104:107], v[44:47], v[116:119]
	v_mfma_f32_16x16x32_f16 v[112:115], v[104:107], v[40:43], v[112:115]
	v_mfma_f32_16x16x32_f16 v[116:119], v[104:107], v[48:51], v[116:119]
	s_waitcnt lgkmcnt(2)
	v_mfma_f32_16x16x32_f16 v[112:115], v[108:111], v[36:39], v[112:115]
	v_mfma_f32_16x16x32_f16 v[116:119], v[108:111], v[44:47], v[116:119]
	s_waitcnt lgkmcnt(1)
	v_mfma_f32_16x16x32_f16 v[112:115], v[120:123], v[52:55], v[112:115]
	v_mfma_f32_16x16x32_f16 v[116:119], v[120:123], v[60:63], v[116:119]
	v_mfma_f32_16x16x32_f16 v[112:115], v[120:123], v[56:59], v[112:115]
	v_mfma_f32_16x16x32_f16 v[116:119], v[120:123], v[68:71], v[116:119]
	s_waitcnt lgkmcnt(0)
	v_mfma_f32_16x16x32_f16 v[112:115], v[124:127], v[52:55], v[112:115]
	v_mfma_f32_16x16x32_f16 v[116:119], v[124:127], v[60:63], v[116:119]
	s_branch .Lr2_part

; #define GAS __attribute__((address_space(1)))
; #define LAS __attribute__((address_space(3)))
; __device__ __forceinline__ float ex2(float x) { return __builtin_amdgcn_exp2f(x); }
; __device__ __forceinline__ float row16_max(float v) { v = fmaxf(v, dpp_f<0xB1>(v)); v = fmaxf(v, dpp_f<0x4E>(v)); v = fmaxf(v, dpp_f<0x141>(v)); v = fmaxf(v, dpp_f<0x140>(v)); return v; }
; __device__ __forceinline__ void p_r2(const Args& a, LAS unsigned char* lds, volatile LAS unsigned* MISC, int l, int wg, int G, int wave, int lane, int tid) {
;     ...
;             float sgm = rbias;
; #pragma unroll
;             for (int w = 0; w < 8; ++w) sgm += PART[(w * 16 + (tid >> 5)) * 32 + (tid & 31)];
;             { const int half = lane >> 5, ee = lane & 31; float lg = sgm;
;               int si[4]; float sv[4];
; #pragma unroll
;               for (int k = 0; k < 4; ++k) { float mx = row16_max(lg); mx = fmaxf(mx, __shfl_xor(mx, 16)); const unsigned long long bal = __ballot(lg == mx);
;                   const unsigned bits = half ? (unsigned)(bal >> 32) : (unsigned)bal; si[k] = __ffs((int)bits) - 1; sv[k] = mx; if (ee == si[k]) lg = -3.0e38f; }
;               const float e1 = ex2((sv[1] - sv[0]) * LOG2E), e2 = ex2((sv[2] - sv[0]) * LOG2E), e3 = ex2((sv[3] - sv[0]) * LOG2E), inv = 1.0f / (1.0f + e1 + e2 + e3);
;               if (ee == 0) { const int t = tb + 2 * wave + half;
;                   *(LAS v4i*)(lds + R2_TOP + (t - 256 * chunk) * 16) = (v4i){si[0], si[1], si[2], si[3]}; *(LAS f32x4*)(lds + R2_TOP + 4096 + (t - 256 * chunk) * 16) = (f32x4){inv, e1 * inv, e2 * inv, e3 * inv};
; #pragma unroll
;                   for (int k = 0; k < 4; ++k) __hip_atomic_fetch_add((LAS unsigned*)(MISC + MW_HIST + si[k]), 1u, __ATOMIC_RELAXED, __HIP_MEMORY_SCOPE_WORKGROUP); } }
;         }
;         __syncthreads();
;         if (tid < 256) { *(GAS v4i*)(TOPI + (size_t)(256 * chunk + tid) * 4) = *(const LAS v4i*)(lds + R2_TOP + tid * 16); *(GAS f32x4*)(TOPW + (size_t)(256 * chunk + tid) * 4) = *(const LAS f32x4*)(lds + R2_TOP + 4096 + tid * 16); }
.LBB0_840:
	ds_read2st64_b32 v[144:145], v65 offset1:8
	ds_read2st64_b32 v[146:147], v65 offset0:16 offset1:24
	ds_read2st64_b32 v[148:149], v65 offset0:32 offset1:40
	ds_read2st64_b32 v[150:151], v65 offset0:48 offset1:56
	s_waitcnt lgkmcnt(0)
	v_add_f32_e32 v128, v167, v144
	v_add_f32_e32 v128, v128, v145
	v_add_f32_e32 v128, v128, v146
	v_add_f32_e32 v128, v128, v147
	v_add_f32_e32 v128, v128, v148
	v_add_f32_e32 v128, v128, v149
	v_add_f32_e32 v128, v128, v150
	v_add_f32_e32 v128, v128, v151
	s_nop 1
	v_max_f32_dpp v129, v128, v128 quad_perm:[1,0,3,2] row_mask:0xf bank_mask:0xf bound_ctrl:1
	s_nop 1
	v_max_f32_dpp v129, v129, v129 quad_perm:[2,3,0,1] row_mask:0xf bank_mask:0xf bound_ctrl:1
	s_nop 1
	v_max_f32_dpp v129, v129, v129 row_half_mirror row_mask:0xf bank_mask:0xf bound_ctrl:1
	s_nop 1
	v_max_f32_dpp v129, v129, v129 row_mirror row_mask:0xf bank_mask:0xf bound_ctrl:1
	v_mov_b32_e32 v142, v129
	s_nop 1
	v_permlane16_swap_b32_e32 v142, v129
	v_max_f32_e32 v129, v129, v142
	v_cmp_eq_f32_e32 vcc, v128, v129
	s_nop 1
	v_lshrrev_b64 v[140:141], v166, vcc
	v_ffbl_b32_e32 v136, v140
	v_cmp_ne_u32_e32 vcc, v67, v136
	s_nop 1
	v_cndmask_b32_e32 v130, v233, v128, vcc
	s_nop 1
	v_max_f32_dpp v131, v130, v130 quad_perm:[1,0,3,2] row_mask:0xf bank_mask:0xf bound_ctrl:1
	s_nop 1
	v_max_f32_dpp v131, v131, v131 quad_perm:[2,3,0,1] row_mask:0xf bank_mask:0xf bound_ctrl:1
	s_nop 1
	v_max_f32_dpp v131, v131, v131 row_half_mirror row_mask:0xf bank_mask:0xf bound_ctrl:1
	s_nop 1
	v_max_f32_dpp v131, v131, v131 row_mirror row_mask:0xf bank_mask:0xf bound_ctrl:1
	v_mov_b32_e32 v142, v131
	s_nop 1
	v_permlane16_swap_b32_e32 v142, v131
	v_max_f32_e32 v131, v131, v142
	v_cmp_eq_f32_e32 vcc, v130, v131
	s_nop 1
	v_lshrrev_b64 v[140:141], v166, vcc
	v_ffbl_b32_e32 v137, v140
	v_cmp_ne_u32_e32 vcc, v67, v137
	s_nop 1
	v_cndmask_b32_e32 v132, v233, v130, vcc
	s_nop 1
	v_max_f32_dpp v133, v132, v132 quad_perm:[1,0,3,2] row_mask:0xf bank_mask:0xf bound_ctrl:1
	s_nop 1
	v_max_f32_dpp v133, v133, v133 quad_perm:[2,3,0,1] row_mask:0xf bank_mask:0xf bound_ctrl:1
	s_nop 1
	v_max_f32_dpp v133, v133, v133 row_half_mirror row_mask:0xf bank_mask:0xf bound_ctrl:1
	s_nop 1
	v_max_f32_dpp v133, v133, v133 row_mirror row_mask:0xf bank_mask:0xf bound_ctrl:1
	v_mov_b32_e32 v142, v133
	s_nop 1
	v_permlane16_swap_b32_e32 v142, v133
	v_max_f32_e32 v133, v133, v142
	v_cmp_eq_f32_e32 vcc, v132, v133
	s_nop 1
	v_lshrrev_b64 v[140:141], v166, vcc
	v_ffbl_b32_e32 v138, v140
	v_cmp_ne_u32_e32 vcc, v67, v138
	s_nop 1
	v_cndmask_b32_e32 v134, v233, v132, vcc
	s_nop 1
	v_max_f32_dpp v135, v134, v134 quad_perm:[1,0,3,2] row_mask:0xf bank_mask:0xf bound_ctrl:1
	s_nop 1
	v_max_f32_dpp v135, v135, v135 quad_perm:[2,3,0,1] row_mask:0xf bank_mask:0xf bound_ctrl:1
	s_nop 1
	v_max_f32_dpp v135, v135, v135 row_half_mirror row_mask:0xf bank_mask:0xf bound_ctrl:1
	s_nop 1
	v_max_f32_dpp v135, v135, v135 row_mirror row_mask:0xf bank_mask:0xf bound_ctrl:1
	v_mov_b32_e32 v142, v135
	s_nop 1
	v_permlane16_swap_b32_e32 v142, v135
	v_max_f32_e32 v135, v135, v142
	v_cmp_eq_f32_e32 vcc, v134, v135
	s_and_saveexec_b64 s[2:3], s[48:49]
	s_cbranch_execz .Lr2_tail_done2
	v_sub_f32_e32 v135, v135, v129
	v_sub_f32_e32 v133, v133, v129
	v_sub_f32_e32 v131, v131, v129
	v_lshrrev_b64 v[140:141], v166, vcc
	v_mul_f32_e32 v131, 0x3fb8aa3b, v131
	v_ffbl_b32_e32 v139, v140
	v_mul_f32_e32 v133, 0x3fb8aa3b, v133
	v_exp_f32_e32 v144, v131
	v_mul_f32_e32 v135, 0x3fb8aa3b, v135
	v_exp_f32_e32 v145, v133
	v_exp_f32_e32 v135, v135
	v_add_f32_e32 v146, 1.0, v144
	v_add_f32_e32 v146, v146, v145
	v_add_f32_e32 v146, v146, v135
	v_div_scale_f32 v147, s[8:9], v146, v146, 1.0
	v_rcp_f32_e32 v148, v147
	s_nop 0
	v_fma_f32 v149, -v147, v148, 1.0
	v_fmac_f32_e32 v148, v149, v148
	v_div_scale_f32 v149, vcc, 1.0, v146, 1.0
	v_mul_f32_e32 v150, v149, v148
	v_fma_f32 v151, -v147, v150, v149
	v_fmac_f32_e32 v150, v151, v148
	v_fma_f32 v147, -v147, v150, v149
	v_div_fmas_f32 v147, v147, v148, v150
	v_div_fixup_f32 v148, v147, v146, 1.0
	v_add_u32_e32 v140, 0xffffef00, v185
	ds_write_b128 v140, v[136:139]
	v_mul_f32_e32 v149, v144, v148
	v_mul_f32_e32 v150, v145, v148
	v_mul_f32_e32 v151, v135, v148
	v_add_u32_e32 v141, 0xffffff00, v185
	ds_write_b128 v141, v[148:151]
	v_lshl_add_u32 v140, v136, 2, s26
	ds_add_u32 v140, v201
	v_lshl_add_u32 v140, v137, 2, s26
	ds_add_u32 v140, v201
	v_lshl_add_u32 v140, v138, 2, s26
	ds_add_u32 v140, v201
	v_lshl_add_u32 v140, v139, 2, s26
	ds_add_u32 v140, v201
.Lr2_tail_done2:
	s_or_b64 exec, exec, s[2:3]
	s_waitcnt lgkmcnt(0)
	s_barrier
	s_and_saveexec_b64 s[2:3], s[50:51]
	s_cbranch_execz .LBB0_842
	v_add_u32_e32 v17, 0, v157
	v_add_u32_e32 v72, 0x1a000, v17
	ds_read_b128 v[72:75], v72
	v_add_u32_e32 v18, s36, v64
	v_ashrrev_i32_e32 v19, 31, v18
	v_readlane_b32 s8, v252, 15
	v_lshlrev_b64 v[18:19], 4, v[18:19]
	v_readlane_b32 s9, v252, 16
	v_add_u32_e32 v17, 0x1b000, v17
	s_nop 0
	v_lshl_add_u64 v[76:77], s[8:9], 0, v[18:19]
	s_waitcnt lgkmcnt(0)
	global_store_dwordx4 v[76:77], v[72:75], off
	ds_read_b128 v[72:75], v17
	v_lshl_add_u64 v[18:19], s[28:29], 0, v[18:19]
	s_waitcnt lgkmcnt(0)
	global_store_dwordx4 v[18:19], v[72:75], off
